# v50 + P7 gate epilogue: next row group's ss load issued one group ahead (v251), the per-group vmcnt(0) in front of its use dropped
# baseline (speedup 1.0000x reference)
; __device__ __forceinline__ unsigned cvt_pk_bf16(float lo, float hi) { unsigned r; asm volatile("v_cvt_pk_bf16_f32 %0, %1, %2" : "=v"(r) : "v"(lo), "v"(hi)); return r; }
; template <bool WT> __device__ __forceinline__ void st16(void* p, f32x4 v) { if constexpr (WT) st16_wt(p, v); else *(f32x4*)p = v; }
; __device__ __forceinline__ float rstd_of(float ss) { return __builtin_amdgcn_rsqf(ss * (1.0f / 2048.0f) + NORM_EPS); }
;     __device__ __forceinline__ void operator()(const f32x4 (&acc)[2][2][4][2], const Unit& u, int wr, int wc, int fr, int fq) const {
;     ...
;             for (int m = 0; m < 4; ++m) { const size_t ro = (size_t)(ai * HALF + m * 16) * LD; float sq = 0.f; const int grow = u.pm * BM + ai * HALF + m * 16 + rt; const float rs = rstd_of(ssin[grow]);
; #pragma unroll
;                 for (int bj = 0; bj < 2; ++bj) { const size_t o = obase + ro + bj * HALF; const f32x4 h0 = *(const f32x4*)(H + o), h1 = *(const f32x4*)(H + o + 4); const u32x4 ev = *(const u32x4*)(E + o);
;                     const f32x4 a0 = acc[ai][bj][m][0] * rs, a1 = acc[ai][bj][m][1] * rs; f32x4 v0, v1;
;                     v0[0] = h0[0] + sigmoid_f(a0[0]) * __uint_as_float(ev.x << 16); v0[1] = h0[1] + sigmoid_f(a0[1]) * __uint_as_float(ev.x & 0xffff0000u);
;                     v0[2] = h0[2] + sigmoid_f(a0[2]) * __uint_as_float(ev.y << 16); v0[3] = h0[3] + sigmoid_f(a0[3]) * __uint_as_float(ev.y & 0xffff0000u);
;                     v1[0] = h1[0] + sigmoid_f(a1[0]) * __uint_as_float(ev.z << 16); v1[1] = h1[1] + sigmoid_f(a1[1]) * __uint_as_float(ev.z & 0xffff0000u);
;                     v1[2] = h1[2] + sigmoid_f(a1[2]) * __uint_as_float(ev.w << 16); v1[3] = h1[3] + sigmoid_f(a1[3]) * __uint_as_float(ev.w & 0xffff0000u);
;                     st16<WT>(H + o, v0); st16<WT>(H + o + 4, v1);
;                     if constexpr (WXB) { u32x4 w; w.x = cvt_pk_bf16(v0[0], v0[1]); w.y = cvt_pk_bf16(v0[2], v0[3]); w.z = cvt_pk_bf16(v1[0], v1[1]); w.w = cvt_pk_bf16(v1[2], v1[3]);
;                         st16<WT>(XB + o, __builtin_bit_cast(f32x4, w)); }
;                     sq += (v0[0] * v0[0] + v0[1] * v0[1]) + (v0[2] * v0[2] + v0[3] * v0[3]) + (v1[0] * v1[0] + v1[1] * v1[1]) + (v1[2] * v1[2] + v1[3] * v1[3]); }
;                 sq += __shfl_xor(sq, 16); sq += __shfl_xor(sq, 32);
;                 if (fq == 0) ss_add<false>(ssout + grow, sq);
.LBB0_719:
	s_lshl_b32 s16, s12, 8
	v_add_u32_e32 v160, s16, v174
	v_lshl_add_u32 v128, s10, 8, v176
	v_ashrrev_i32_e32 v161, 31, v160
	v_lshlrev_b64 v[130:131], 11, v[160:161]
	v_ashrrev_i32_e32 v129, 31, v128
	v_lshl_add_u64 v[132:133], v[130:131], 0, v[128:129]
	v_lshl_add_u64 v[128:129], v[160:161], 2, s[58:59]
	global_load_dword v146, v[128:129], off
	v_lshlrev_b64 v[154:155], 1, v[132:133]
	v_lshl_add_u64 v[158:159], s[8:9], 0, v[154:155]
	global_load_dwordx4 v[128:131], v[158:159], off
	v_readlane_b32 s16, v249, 1
	v_readlane_b32 s17, v249, 2
	s_waitcnt vmcnt(0)
	v_fmamk_f32 v146, v146, 0x3a000000, v181
	v_lshl_add_u64 v[156:157], v[132:133], 2, s[16:17]
	global_load_dwordx4 v[132:135], v[156:157], off
	global_load_dwordx4 v[136:139], v[156:157], off offset:16
	v_rsq_f32_e32 v146, v146
	v_lshlrev_b32_e32 v164, 16, v128
	v_and_b32_e32 v165, 0xffff0000, v128
	v_lshlrev_b32_e32 v166, 16, v129
	v_and_b32_e32 v167, 0xffff0000, v129
	v_lshlrev_b32_e32 v168, 16, v130
	v_and_b32_e32 v169, 0xffff0000, v130
	v_lshlrev_b32_e32 v170, 16, v131
	v_and_b32_e32 v171, 0xffff0000, v131
	v_pk_mul_f32 v[128:129], v[126:127], v[146:147] op_sel_hi:[1,0]
	v_pk_mul_f32 v[130:131], v[124:125], v[146:147] op_sel_hi:[1,0]
	v_pk_mul_f32 v[172:173], v[122:123], v[146:147] op_sel_hi:[1,0]
	v_pk_mul_f32 v[182:183], v[120:121], v[146:147] op_sel_hi:[1,0]
	v_mul_f32_e32 v130, 0xbfb8aa3b, v130
	v_mul_f32_e32 v131, 0xbfb8aa3b, v131
	v_mul_f32_e32 v128, 0xbfb8aa3b, v128
	v_mul_f32_e32 v129, 0xbfb8aa3b, v129
	v_mul_f32_e32 v182, 0xbfb8aa3b, v182
	v_mul_f32_e32 v183, 0xbfb8aa3b, v183
	v_mul_f32_e32 v172, 0xbfb8aa3b, v172
	v_mul_f32_e32 v173, 0xbfb8aa3b, v173
	v_exp_f32_e32 v130, v130
	v_exp_f32_e32 v131, v131
	v_exp_f32_e32 v128, v128
	v_exp_f32_e32 v129, v129
	v_exp_f32_e32 v182, v182
	v_exp_f32_e32 v183, v183
	v_exp_f32_e32 v172, v172
	v_exp_f32_e32 v173, v173
	v_add_f32_e32 v130, 1.0, v130
	v_add_f32_e32 v131, 1.0, v131
	v_add_f32_e32 v184, 1.0, v128
	v_add_f32_e32 v185, 1.0, v129
	v_add_f32_e32 v182, 1.0, v182
	v_add_f32_e32 v183, 1.0, v183
	v_add_f32_e32 v186, 1.0, v172
	v_add_f32_e32 v187, 1.0, v173
	v_rcp_f32_e32 v128, v130
	v_rcp_f32_e32 v129, v131
	v_rcp_f32_e32 v130, v184
	v_rcp_f32_e32 v131, v185
	v_rcp_f32_e32 v172, v182
	v_rcp_f32_e32 v173, v183
	v_rcp_f32_e32 v182, v186
	v_rcp_f32_e32 v183, v187
	v_readlane_b32 s16, v250, 63
	v_readlane_b32 s17, v249, 0
	v_lshl_add_u64 v[162:163], v[156:157], 0, 16
	v_pk_mul_f32 v[184:185], v[92:93], v[146:147] op_sel_hi:[1,0]
	v_lshl_add_u64 v[154:155], s[16:17], 0, v[154:155]
	v_pk_mul_f32 v[186:187], v[90:91], v[146:147] op_sel_hi:[1,0]
	v_pk_mul_f32 v[188:189], v[88:89], v[146:147] op_sel_hi:[1,0]
	v_mul_f32_e32 v186, 0xbfb8aa3b, v186
	v_mul_f32_e32 v187, 0xbfb8aa3b, v187
	v_exp_f32_e32 v186, v186
	v_exp_f32_e32 v187, v187
	s_mov_b64 s[16:17], 0x200
	v_add_f32_e32 v192, 1.0, v186
	v_add_f32_e32 v193, 1.0, v187
	s_waitcnt vmcnt(1)
	v_pk_fma_f32 v[128:129], v[128:129], v[164:165], v[132:133]
	v_pk_fma_f32 v[130:131], v[130:131], v[166:167], v[134:135]
	s_waitcnt vmcnt(0)
	v_pk_fma_f32 v[132:133], v[172:173], v[168:169], v[136:137]
	global_store_dwordx4 v[156:157], v[128:131], off sc1
	s_nop 1
	v_pk_fma_f32 v[134:135], v[182:183], v[170:171], v[138:139]
	v_pk_mul_f32 v[182:183], v[94:95], v[146:147] op_sel_hi:[1,0]
	global_store_dwordx4 v[162:163], v[132:135], off sc1
	s_nop 1
	v_cvt_pk_bf16_f32 v136, v128, v129
	v_cvt_pk_bf16_f32 v137, v130, v131
	v_cvt_pk_bf16_f32 v138, v132, v133
	v_cvt_pk_bf16_f32 v139, v134, v135
	v_mul_f32_e32 v146, 0xbfb8aa3b, v184
	global_store_dwordx4 v[154:155], v[136:139], off sc1
	s_nop 1
	global_load_dwordx4 v[136:139], v[158:159], off offset:256
	global_load_dwordx4 v[162:165], v[156:157], off offset:512
	global_load_dwordx4 v[166:169], v[156:157], off offset:528
	v_mul_f32_e32 v184, 0xbfb8aa3b, v185
	v_mul_f32_e32 v182, 0xbfb8aa3b, v182
	v_mul_f32_e32 v183, 0xbfb8aa3b, v183
	v_mul_f32_e32 v185, 0xbfb8aa3b, v188
	v_mul_f32_e32 v188, 0xbfb8aa3b, v189
	v_exp_f32_e32 v146, v146
	v_exp_f32_e32 v184, v184
	v_exp_f32_e32 v182, v182
	v_exp_f32_e32 v183, v183
	v_exp_f32_e32 v185, v185
	v_exp_f32_e32 v188, v188
	v_add_f32_e32 v146, 1.0, v146
	v_add_f32_e32 v184, 1.0, v184
	v_add_f32_e32 v189, 1.0, v182
	v_add_f32_e32 v190, 1.0, v183
	v_pk_mul_f32 v[128:129], v[128:129], v[128:129]
	v_pk_mul_f32 v[130:131], v[130:131], v[130:131]
	v_add_f32_e32 v191, 1.0, v185
	v_add_f32_e32 v188, 1.0, v188
	v_rcp_f32_e32 v182, v146
	v_rcp_f32_e32 v183, v184
	v_rcp_f32_e32 v184, v189
	v_rcp_f32_e32 v185, v190
	v_pk_mul_f32 v[132:133], v[132:133], v[132:133]
	v_add_f32_e32 v130, v130, v131
	v_add_f32_e32 v128, v128, v129
	v_rcp_f32_e32 v186, v191
	v_rcp_f32_e32 v187, v188
	v_pk_mul_f32 v[134:135], v[134:135], v[134:135]
	v_add_f32_e32 v129, v132, v133
	v_add_f32_e32 v128, v128, v130
	v_rcp_f32_e32 v188, v192
	v_rcp_f32_e32 v189, v193
	v_add_f32_e32 v134, v134, v135
	v_add_f32_e32 v128, v129, v128
	v_add_f32_e32 v146, v134, v128
	v_lshl_add_u64 v[170:171], v[156:157], 0, s[16:17]
	s_mov_b64 s[16:17], 0x210
	v_lshl_add_u64 v[172:173], v[156:157], 0, s[16:17]
	s_mov_b64 s[16:17], 0x100
	s_waitcnt vmcnt(2)
	v_lshlrev_b32_e32 v128, 16, v136
	v_and_b32_e32 v129, 0xffff0000, v136
	v_lshlrev_b32_e32 v130, 16, v137
	v_and_b32_e32 v131, 0xffff0000, v137
	v_lshlrev_b32_e32 v132, 16, v138
	v_and_b32_e32 v133, 0xffff0000, v138
	s_waitcnt vmcnt(1)
	v_pk_fma_f32 v[128:129], v[182:183], v[128:129], v[162:163]
	v_pk_fma_f32 v[130:131], v[184:185], v[130:131], v[164:165]
	v_lshlrev_b32_e32 v134, 16, v139
	v_and_b32_e32 v135, 0xffff0000, v139
	s_waitcnt vmcnt(0)
	v_pk_fma_f32 v[132:133], v[186:187], v[132:133], v[166:167]
	global_store_dwordx4 v[170:171], v[128:131], off sc1
	s_nop 1
	v_pk_mul_f32 v[138:139], v[128:129], v[128:129]
	v_pk_mul_f32 v[162:163], v[130:131], v[130:131]
	v_pk_fma_f32 v[134:135], v[188:189], v[134:135], v[168:169]
	v_pk_mul_f32 v[164:165], v[132:133], v[132:133]
	global_store_dwordx4 v[172:173], v[132:135], off sc1
	s_nop 1
	v_cvt_pk_bf16_f32 v136, v128, v129
	v_add_f32_e32 v129, v162, v163
	v_add_f32_e32 v137, v138, v139
	v_pk_mul_f32 v[166:167], v[134:135], v[134:135]
	v_add_f32_e32 v129, v137, v129
	v_add_f32_e32 v137, v164, v165
	v_add_f32_e32 v128, v166, v167
	v_add_f32_e32 v129, v137, v129
	v_add_f32_e32 v128, v128, v129
	v_add_f32_e32 v128, v146, v128
	ds_bpermute_b32 v129, v177, v128
	v_cvt_pk_bf16_f32 v137, v130, v131
	v_cvt_pk_bf16_f32 v138, v132, v133
	v_cvt_pk_bf16_f32 v139, v134, v135
	v_lshl_add_u64 v[130:131], v[154:155], 0, s[16:17]
	s_waitcnt lgkmcnt(0)
	v_add_f32_e32 v128, v128, v129
	ds_bpermute_b32 v129, v178, v128
	global_store_dwordx4 v[130:131], v[136:139], off sc1
	s_nop 1
	v_or_b32_e32 v254, 16, v160
	v_ashrrev_i32_e32 v255, 31, v254
	v_lshl_add_u64 v[252:253], v[254:255], 2, s[58:59]
	global_load_dword v251, v[252:253], off
	s_and_saveexec_b64 s[16:17], s[6:7]
	s_cbranch_execz .LBB0_721
	v_lshl_add_u64 v[130:131], v[160:161], 2, s[60:61]
	s_waitcnt lgkmcnt(0)
	v_add_f32_e32 v128, v128, v129
	global_atomic_add_f32 v[130:131], v128, off
; __device__ __forceinline__ unsigned cvt_pk_bf16(float lo, float hi) { unsigned r; asm volatile("v_cvt_pk_bf16_f32 %0, %1, %2" : "=v"(r) : "v"(lo), "v"(hi)); return r; }
; template <bool WT> __device__ __forceinline__ void st16(void* p, f32x4 v) { if constexpr (WT) st16_wt(p, v); else *(f32x4*)p = v; }
; __device__ __forceinline__ float rstd_of(float ss) { return __builtin_amdgcn_rsqf(ss * (1.0f / 2048.0f) + NORM_EPS); }
;     __device__ __forceinline__ void operator()(const f32x4 (&acc)[2][2][4][2], const Unit& u, int wr, int wc, int fr, int fq) const {
;     ...
;             for (int m = 0; m < 4; ++m) { const size_t ro = (size_t)(ai * HALF + m * 16) * LD; float sq = 0.f; const int grow = u.pm * BM + ai * HALF + m * 16 + rt; const float rs = rstd_of(ssin[grow]);
; #pragma unroll
;                 for (int bj = 0; bj < 2; ++bj) { const size_t o = obase + ro + bj * HALF; const f32x4 h0 = *(const f32x4*)(H + o), h1 = *(const f32x4*)(H + o + 4); const u32x4 ev = *(const u32x4*)(E + o);
;                     const f32x4 a0 = acc[ai][bj][m][0] * rs, a1 = acc[ai][bj][m][1] * rs; f32x4 v0, v1;
;                     v0[0] = h0[0] + sigmoid_f(a0[0]) * __uint_as_float(ev.x << 16); v0[1] = h0[1] + sigmoid_f(a0[1]) * __uint_as_float(ev.x & 0xffff0000u);
;                     v0[2] = h0[2] + sigmoid_f(a0[2]) * __uint_as_float(ev.y << 16); v0[3] = h0[3] + sigmoid_f(a0[3]) * __uint_as_float(ev.y & 0xffff0000u);
;                     v1[0] = h1[0] + sigmoid_f(a1[0]) * __uint_as_float(ev.z << 16); v1[1] = h1[1] + sigmoid_f(a1[1]) * __uint_as_float(ev.z & 0xffff0000u);
;                     v1[2] = h1[2] + sigmoid_f(a1[2]) * __uint_as_float(ev.w << 16); v1[3] = h1[3] + sigmoid_f(a1[3]) * __uint_as_float(ev.w & 0xffff0000u);
;                     st16<WT>(H + o, v0); st16<WT>(H + o + 4, v1);
;                     if constexpr (WXB) { u32x4 w; w.x = cvt_pk_bf16(v0[0], v0[1]); w.y = cvt_pk_bf16(v0[2], v0[3]); w.z = cvt_pk_bf16(v1[0], v1[1]); w.w = cvt_pk_bf16(v1[2], v1[3]);
;                         st16<WT>(XB + o, __builtin_bit_cast(f32x4, w)); }
;                     sq += (v0[0] * v0[0] + v0[1] * v0[1]) + (v0[2] * v0[2] + v0[3] * v0[3]) + (v1[0] * v1[0] + v1[1] * v1[1]) + (v1[2] * v1[2] + v1[3] * v1[3]); }
;                 sq += __shfl_xor(sq, 16); sq += __shfl_xor(sq, 32);
;                 if (fq == 0) ss_add<false>(ssout + grow, sq);
.LBB0_721:
	s_or_b64 exec, exec, s[16:17]
	v_or_b32_e32 v162, 16, v160
	v_ashrrev_i32_e32 v163, 31, v162
	s_waitcnt lgkmcnt(0)
	v_add_co_u32_e32 v166, vcc, 0x20000, v156
	s_mov_b64 s[16:17], 0x20010
	s_nop 0
	v_addc_co_u32_e32 v167, vcc, 0, v157, vcc
	v_lshl_add_u64 v[170:171], v[156:157], 0, s[16:17]
	s_mov_b32 s16, 0x10000
	v_add_co_u32_e32 v164, vcc, s16, v158
	v_lshl_add_u64 v[168:169], v[156:157], 0, s[68:69]
	s_nop 0
	v_addc_co_u32_e32 v165, vcc, 0, v159, vcc
	s_mov_b64 s[16:17], 0x10000
	s_waitcnt vmcnt(1)
	v_fmamk_f32 v128, v251, 0x3a000000, v181
	v_or_b32_e32 v254, 32, v160
	v_ashrrev_i32_e32 v255, 31, v254
	v_lshl_add_u64 v[252:253], v[254:255], 2, s[58:59]
	global_load_dword v251, v[252:253], off
	v_rsq_f32_e32 v146, v128
	global_load_dwordx4 v[128:131], v[166:167], off
	global_load_dwordx4 v[132:135], v[168:169], off offset:16
	global_load_dwordx4 v[136:139], v[164:165], off
	v_pk_mul_f32 v[172:173], v[118:119], v[146:147] op_sel_hi:[1,0]
	v_pk_mul_f32 v[186:187], v[112:113], v[146:147] op_sel_hi:[1,0]
	v_pk_mul_f32 v[182:183], v[116:117], v[146:147] op_sel_hi:[1,0]
	v_pk_mul_f32 v[184:185], v[114:115], v[146:147] op_sel_hi:[1,0]
	v_mul_f32_e32 v161, 0xbfb8aa3b, v182
	v_exp_f32_e32 v161, v161
	v_pk_mul_f32 v[190:191], v[80:81], v[146:147] op_sel_hi:[1,0]
	v_add_f32_e32 v161, 1.0, v161
	v_rcp_f32_e32 v182, v161
	v_mul_f32_e32 v161, 0xbfb8aa3b, v183
	v_exp_f32_e32 v161, v161
	s_waitcnt vmcnt(0)
	v_lshlrev_b32_e32 v188, 16, v136
	v_and_b32_e32 v189, 0xffff0000, v136
	v_mul_f32_e32 v136, 0xbfb8aa3b, v172
	v_exp_f32_e32 v136, v136
	v_add_f32_e32 v161, 1.0, v161
	v_rcp_f32_e32 v183, v161
	v_add_f32_e32 v136, 1.0, v136
	v_rcp_f32_e32 v172, v136
	v_mul_f32_e32 v136, 0xbfb8aa3b, v173
	v_exp_f32_e32 v136, v136
	v_pk_fma_f32 v[128:129], v[182:183], v[188:189], v[128:129]
	v_pk_mul_f32 v[188:189], v[82:83], v[146:147] op_sel_hi:[1,0]
	v_add_f32_e32 v136, 1.0, v136
	v_rcp_f32_e32 v173, v136
	v_lshlrev_b32_e32 v136, 16, v137
	v_and_b32_e32 v137, 0xffff0000, v137
	v_pk_fma_f32 v[130:131], v[172:173], v[136:137], v[130:131]
	v_mul_f32_e32 v136, 0xbfb8aa3b, v186
	v_mul_f32_e32 v137, 0xbfb8aa3b, v187
	v_exp_f32_e32 v136, v136
	v_exp_f32_e32 v137, v137
	v_lshlrev_b32_e32 v172, 16, v138
	v_and_b32_e32 v173, 0xffff0000, v138
	v_add_f32_e32 v136, 1.0, v136
	v_add_f32_e32 v137, 1.0, v137
	v_rcp_f32_e32 v136, v136
	v_rcp_f32_e32 v137, v137
	v_lshlrev_b32_e32 v138, 16, v139
	v_and_b32_e32 v139, 0xffff0000, v139
	global_store_dwordx4 v[168:169], v[128:131], off sc1
	s_nop 1
	v_pk_fma_f32 v[132:133], v[136:137], v[172:173], v[132:133]
	v_mul_f32_e32 v136, 0xbfb8aa3b, v184
	v_mul_f32_e32 v137, 0xbfb8aa3b, v185
	v_exp_f32_e32 v136, v136
	v_exp_f32_e32 v137, v137
	v_lshl_add_u64 v[168:169], v[154:155], 0, s[16:17]
	s_mov_b64 s[16:17], 0x20200
	v_add_f32_e32 v136, 1.0, v136
	v_add_f32_e32 v137, 1.0, v137
	v_rcp_f32_e32 v136, v136
	v_rcp_f32_e32 v137, v137
	v_lshl_add_u64 v[172:173], v[156:157], 0, s[16:17]
	v_pk_mul_f32 v[186:187], v[84:85], v[146:147] op_sel_hi:[1,0]
	s_mov_b64 s[16:17], 0x20210
	v_pk_fma_f32 v[134:135], v[136:137], v[138:139], v[134:135]
	s_nop 0
	global_store_dwordx4 v[170:171], v[132:135], off sc1
	s_nop 1
	v_cvt_pk_bf16_f32 v136, v128, v129
	v_cvt_pk_bf16_f32 v137, v130, v131
	v_cvt_pk_bf16_f32 v138, v132, v133
	v_cvt_pk_bf16_f32 v139, v134, v135
	v_pk_mul_f32 v[170:171], v[130:131], v[130:131]
	global_store_dwordx4 v[168:169], v[136:139], off sc1
	s_nop 1
	v_pk_mul_f32 v[168:169], v[128:129], v[128:129]
	v_pk_mul_f32 v[138:139], v[132:133], v[132:133]
	v_pk_mul_f32 v[136:137], v[134:135], v[134:135]
	global_load_dwordx4 v[182:185], v[166:167], off offset:512
	global_load_dwordx4 v[128:131], v[172:173], off offset:16
	global_load_dwordx4 v[132:135], v[164:165], off offset:256
	v_pk_mul_f32 v[164:165], v[86:87], v[146:147] op_sel_hi:[1,0]
	v_mul_f32_e32 v146, 0xbfb8aa3b, v186
	v_exp_f32_e32 v146, v146
	v_lshl_add_u64 v[166:167], v[156:157], 0, s[16:17]
	s_mov_b64 s[16:17], 0x10100
	v_add_f32_e32 v161, v168, v169
	v_add_f32_e32 v146, 1.0, v146
	v_rcp_f32_e32 v186, v146
	v_mul_f32_e32 v146, 0xbfb8aa3b, v187
	v_exp_f32_e32 v146, v146
	v_add_f32_e32 v138, v138, v139
	v_add_f32_e32 v136, v136, v137
	v_add_f32_e32 v146, 1.0, v146
	v_rcp_f32_e32 v187, v146
	v_add_f32_e32 v146, v170, v171
	v_add_f32_e32 v146, v161, v146
	v_add_f32_e32 v138, v138, v146
	v_add_f32_e32 v136, v136, v138
	s_waitcnt vmcnt(0)
	v_lshlrev_b32_e32 v192, 16, v132
	v_and_b32_e32 v193, 0xffff0000, v132
	v_mul_f32_e32 v132, 0xbfb8aa3b, v164
	v_exp_f32_e32 v132, v132
	v_pk_fma_f32 v[182:183], v[186:187], v[192:193], v[182:183]
	v_add_f32_e32 v132, 1.0, v132
	v_rcp_f32_e32 v164, v132
	v_mul_f32_e32 v132, 0xbfb8aa3b, v165
	v_exp_f32_e32 v132, v132
	s_nop 0
	v_add_f32_e32 v132, 1.0, v132
	v_rcp_f32_e32 v165, v132
	v_lshlrev_b32_e32 v132, 16, v133
	v_and_b32_e32 v133, 0xffff0000, v133
	v_pk_fma_f32 v[184:185], v[164:165], v[132:133], v[184:185]
	v_mul_f32_e32 v132, 0xbfb8aa3b, v190
	v_mul_f32_e32 v133, 0xbfb8aa3b, v191
	v_exp_f32_e32 v132, v132
	v_exp_f32_e32 v133, v133
	v_lshlrev_b32_e32 v164, 16, v134
	v_and_b32_e32 v165, 0xffff0000, v134
	v_add_f32_e32 v132, 1.0, v132
	v_add_f32_e32 v133, 1.0, v133
	v_rcp_f32_e32 v132, v132
	v_rcp_f32_e32 v133, v133
	v_lshlrev_b32_e32 v134, 16, v135
	v_and_b32_e32 v135, 0xffff0000, v135
	global_store_dwordx4 v[172:173], v[182:185], off sc1
	s_nop 1
	v_pk_fma_f32 v[128:129], v[132:133], v[164:165], v[128:129]
	v_mul_f32_e32 v132, 0xbfb8aa3b, v188
	v_mul_f32_e32 v133, 0xbfb8aa3b, v189
	v_exp_f32_e32 v132, v132
	v_exp_f32_e32 v133, v133
	v_lshl_add_u64 v[164:165], v[154:155], 0, s[16:17]
	v_add_f32_e32 v132, 1.0, v132
	v_add_f32_e32 v133, 1.0, v133
	v_rcp_f32_e32 v132, v132
	v_rcp_f32_e32 v133, v133
	s_nop 0
	v_pk_fma_f32 v[130:131], v[132:133], v[134:135], v[130:131]
	s_nop 0
	global_store_dwordx4 v[166:167], v[128:131], off sc1
	s_nop 1
	v_cvt_pk_bf16_f32 v132, v182, v183
	v_cvt_pk_bf16_f32 v133, v184, v185
	v_cvt_pk_bf16_f32 v134, v128, v129
	v_cvt_pk_bf16_f32 v135, v130, v131
	v_pk_mul_f32 v[128:129], v[128:129], v[128:129]
	global_store_dwordx4 v[164:165], v[132:135], off sc1
	s_nop 1
	v_pk_mul_f32 v[132:133], v[182:183], v[182:183]
	v_pk_mul_f32 v[134:135], v[184:185], v[184:185]
	v_add_f32_e32 v132, v132, v133
	v_add_f32_e32 v134, v134, v135
	v_pk_mul_f32 v[130:131], v[130:131], v[130:131]
	v_add_f32_e32 v132, v132, v134
	v_add_f32_e32 v128, v128, v129
	v_add_f32_e32 v128, v128, v132
	v_add_f32_e32 v129, v130, v131
	v_add_f32_e32 v128, v129, v128
	v_add_f32_e32 v128, v136, v128
	ds_bpermute_b32 v129, v177, v128
	s_waitcnt lgkmcnt(0)
	v_add_f32_e32 v128, v128, v129
	ds_bpermute_b32 v129, v178, v128
	s_and_saveexec_b64 s[16:17], s[6:7]
	s_cbranch_execz .LBB0_723
	v_lshl_add_u64 v[130:131], v[162:163], 2, s[60:61]
	s_waitcnt lgkmcnt(0)
	v_add_f32_e32 v128, v128, v129
	global_atomic_add_f32 v[130:131], v128, off
; __device__ __forceinline__ unsigned cvt_pk_bf16(float lo, float hi) { unsigned r; asm volatile("v_cvt_pk_bf16_f32 %0, %1, %2" : "=v"(r) : "v"(lo), "v"(hi)); return r; }
; template <bool WT> __device__ __forceinline__ void st16(void* p, f32x4 v) { if constexpr (WT) st16_wt(p, v); else *(f32x4*)p = v; }
; __device__ __forceinline__ float rstd_of(float ss) { return __builtin_amdgcn_rsqf(ss * (1.0f / 2048.0f) + NORM_EPS); }
;     __device__ __forceinline__ void operator()(const f32x4 (&acc)[2][2][4][2], const Unit& u, int wr, int wc, int fr, int fq) const {
;     ...
;             for (int m = 0; m < 4; ++m) { const size_t ro = (size_t)(ai * HALF + m * 16) * LD; float sq = 0.f; const int grow = u.pm * BM + ai * HALF + m * 16 + rt; const float rs = rstd_of(ssin[grow]);
; #pragma unroll
;                 for (int bj = 0; bj < 2; ++bj) { const size_t o = obase + ro + bj * HALF; const f32x4 h0 = *(const f32x4*)(H + o), h1 = *(const f32x4*)(H + o + 4); const u32x4 ev = *(const u32x4*)(E + o);
;                     const f32x4 a0 = acc[ai][bj][m][0] * rs, a1 = acc[ai][bj][m][1] * rs; f32x4 v0, v1;
;                     v0[0] = h0[0] + sigmoid_f(a0[0]) * __uint_as_float(ev.x << 16); v0[1] = h0[1] + sigmoid_f(a0[1]) * __uint_as_float(ev.x & 0xffff0000u);
;                     v0[2] = h0[2] + sigmoid_f(a0[2]) * __uint_as_float(ev.y << 16); v0[3] = h0[3] + sigmoid_f(a0[3]) * __uint_as_float(ev.y & 0xffff0000u);
;                     v1[0] = h1[0] + sigmoid_f(a1[0]) * __uint_as_float(ev.z << 16); v1[1] = h1[1] + sigmoid_f(a1[1]) * __uint_as_float(ev.z & 0xffff0000u);
;                     v1[2] = h1[2] + sigmoid_f(a1[2]) * __uint_as_float(ev.w << 16); v1[3] = h1[3] + sigmoid_f(a1[3]) * __uint_as_float(ev.w & 0xffff0000u);
;                     st16<WT>(H + o, v0); st16<WT>(H + o + 4, v1);
;                     if constexpr (WXB) { u32x4 w; w.x = cvt_pk_bf16(v0[0], v0[1]); w.y = cvt_pk_bf16(v0[2], v0[3]); w.z = cvt_pk_bf16(v1[0], v1[1]); w.w = cvt_pk_bf16(v1[2], v1[3]);
;                         st16<WT>(XB + o, __builtin_bit_cast(f32x4, w)); }
;                     sq += (v0[0] * v0[0] + v0[1] * v0[1]) + (v0[2] * v0[2] + v0[3] * v0[3]) + (v1[0] * v1[0] + v1[1] * v1[1]) + (v1[2] * v1[2] + v1[3] * v1[3]); }
;                 sq += __shfl_xor(sq, 16); sq += __shfl_xor(sq, 32);
;                 if (fq == 0) ss_add<false>(ssout + grow, sq);
.LBB0_723:
	s_or_b64 exec, exec, s[16:17]
	v_or_b32_e32 v162, 32, v160
	v_ashrrev_i32_e32 v163, 31, v162
	s_waitcnt lgkmcnt(0)
	s_mov_b64 s[16:17], 0x40000
	v_lshl_add_u64 v[168:169], v[156:157], 0, s[16:17]
	v_add_co_u32_e32 v166, vcc, 0x40000, v156
	s_mov_b64 s[16:17], 0x40010
	s_nop 0
	v_addc_co_u32_e32 v167, vcc, 0, v157, vcc
	v_lshl_add_u64 v[170:171], v[156:157], 0, s[16:17]
	s_mov_b32 s16, 0x20000
	v_add_co_u32_e32 v164, vcc, s16, v158
	s_mov_b64 s[16:17], 0x40200
	s_nop 0
	v_addc_co_u32_e32 v165, vcc, 0, v159, vcc
	v_fmamk_f32 v128, v251, 0x3a000000, v181
	v_or_b32_e32 v254, 48, v160
	v_ashrrev_i32_e32 v255, 31, v254
	v_lshl_add_u64 v[252:253], v[254:255], 2, s[58:59]
	global_load_dword v251, v[252:253], off
	v_rsq_f32_e32 v146, v128
	global_load_dwordx4 v[128:131], v[166:167], off
	global_load_dwordx4 v[132:135], v[168:169], off offset:16
	global_load_dwordx4 v[136:139], v[164:165], off
	v_pk_mul_f32 v[172:173], v[110:111], v[146:147] op_sel_hi:[1,0]
	v_pk_mul_f32 v[186:187], v[104:105], v[146:147] op_sel_hi:[1,0]
	v_pk_mul_f32 v[182:183], v[108:109], v[146:147] op_sel_hi:[1,0]
	v_pk_mul_f32 v[184:185], v[106:107], v[146:147] op_sel_hi:[1,0]
	v_mul_f32_e32 v161, 0xbfb8aa3b, v182
	v_exp_f32_e32 v161, v161
	v_pk_mul_f32 v[190:191], v[72:73], v[146:147] op_sel_hi:[1,0]
	v_add_f32_e32 v161, 1.0, v161
	v_rcp_f32_e32 v182, v161
	v_mul_f32_e32 v161, 0xbfb8aa3b, v183
	v_exp_f32_e32 v161, v161
	s_waitcnt vmcnt(0)
	v_lshlrev_b32_e32 v188, 16, v136
	v_and_b32_e32 v189, 0xffff0000, v136
	v_mul_f32_e32 v136, 0xbfb8aa3b, v172
	v_exp_f32_e32 v136, v136
	v_add_f32_e32 v161, 1.0, v161
	v_rcp_f32_e32 v183, v161
	v_add_f32_e32 v136, 1.0, v136
	v_rcp_f32_e32 v172, v136
	v_mul_f32_e32 v136, 0xbfb8aa3b, v173
	v_exp_f32_e32 v136, v136
	v_pk_fma_f32 v[128:129], v[182:183], v[188:189], v[128:129]
	v_pk_mul_f32 v[188:189], v[74:75], v[146:147] op_sel_hi:[1,0]
	v_add_f32_e32 v136, 1.0, v136
	v_rcp_f32_e32 v173, v136
	v_lshlrev_b32_e32 v136, 16, v137
	v_and_b32_e32 v137, 0xffff0000, v137
	v_pk_fma_f32 v[130:131], v[172:173], v[136:137], v[130:131]
	v_mul_f32_e32 v136, 0xbfb8aa3b, v186
	v_mul_f32_e32 v137, 0xbfb8aa3b, v187
	v_exp_f32_e32 v136, v136
	v_exp_f32_e32 v137, v137
	v_lshlrev_b32_e32 v172, 16, v138
	v_and_b32_e32 v173, 0xffff0000, v138
	v_add_f32_e32 v136, 1.0, v136
	v_add_f32_e32 v137, 1.0, v137
	v_rcp_f32_e32 v136, v136
	v_rcp_f32_e32 v137, v137
	v_lshlrev_b32_e32 v138, 16, v139
	v_and_b32_e32 v139, 0xffff0000, v139
	global_store_dwordx4 v[168:169], v[128:131], off sc1
	s_nop 1
	v_pk_fma_f32 v[132:133], v[136:137], v[172:173], v[132:133]
	v_mul_f32_e32 v136, 0xbfb8aa3b, v184
	v_mul_f32_e32 v137, 0xbfb8aa3b, v185
	v_exp_f32_e32 v136, v136
	v_exp_f32_e32 v137, v137
	v_lshl_add_u64 v[168:169], v[154:155], 0, s[68:69]
	v_lshl_add_u64 v[172:173], v[156:157], 0, s[16:17]
	v_add_f32_e32 v136, 1.0, v136
	v_add_f32_e32 v137, 1.0, v137
	v_rcp_f32_e32 v136, v136
	v_rcp_f32_e32 v137, v137
	v_pk_mul_f32 v[186:187], v[76:77], v[146:147] op_sel_hi:[1,0]
	s_mov_b64 s[16:17], 0x40210
	v_pk_fma_f32 v[134:135], v[136:137], v[138:139], v[134:135]
	s_nop 0
	global_store_dwordx4 v[170:171], v[132:135], off sc1
	s_nop 1
	v_cvt_pk_bf16_f32 v136, v128, v129
	v_cvt_pk_bf16_f32 v137, v130, v131
	v_cvt_pk_bf16_f32 v138, v132, v133
	v_cvt_pk_bf16_f32 v139, v134, v135
	v_pk_mul_f32 v[170:171], v[130:131], v[130:131]
	global_store_dwordx4 v[168:169], v[136:139], off sc1
	s_nop 1
	v_pk_mul_f32 v[168:169], v[128:129], v[128:129]
	v_pk_mul_f32 v[138:139], v[132:133], v[132:133]
	v_pk_mul_f32 v[136:137], v[134:135], v[134:135]
	global_load_dwordx4 v[182:185], v[166:167], off offset:512
	global_load_dwordx4 v[128:131], v[172:173], off offset:16
	global_load_dwordx4 v[132:135], v[164:165], off offset:256
	v_pk_mul_f32 v[164:165], v[78:79], v[146:147] op_sel_hi:[1,0]
	v_mul_f32_e32 v146, 0xbfb8aa3b, v186
	v_exp_f32_e32 v146, v146
	v_lshl_add_u64 v[166:167], v[156:157], 0, s[16:17]
	s_mov_b64 s[16:17], 0x20100
	v_add_f32_e32 v161, v168, v169
	v_add_f32_e32 v146, 1.0, v146
	v_rcp_f32_e32 v186, v146
	v_mul_f32_e32 v146, 0xbfb8aa3b, v187
	v_exp_f32_e32 v146, v146
	v_add_f32_e32 v138, v138, v139
	v_add_f32_e32 v136, v136, v137
	v_add_f32_e32 v146, 1.0, v146
	v_rcp_f32_e32 v187, v146
	v_add_f32_e32 v146, v170, v171
	v_add_f32_e32 v146, v161, v146
	v_add_f32_e32 v138, v138, v146
	v_add_f32_e32 v136, v136, v138
	s_waitcnt vmcnt(0)
	v_lshlrev_b32_e32 v192, 16, v132
	v_and_b32_e32 v193, 0xffff0000, v132
	v_mul_f32_e32 v132, 0xbfb8aa3b, v164
	v_exp_f32_e32 v132, v132
	v_pk_fma_f32 v[182:183], v[186:187], v[192:193], v[182:183]
	v_add_f32_e32 v132, 1.0, v132
	v_rcp_f32_e32 v164, v132
	v_mul_f32_e32 v132, 0xbfb8aa3b, v165
	v_exp_f32_e32 v132, v132
	s_nop 0
	v_add_f32_e32 v132, 1.0, v132
	v_rcp_f32_e32 v165, v132
	v_lshlrev_b32_e32 v132, 16, v133
	v_and_b32_e32 v133, 0xffff0000, v133
	v_pk_fma_f32 v[184:185], v[164:165], v[132:133], v[184:185]
	v_mul_f32_e32 v132, 0xbfb8aa3b, v190
	v_mul_f32_e32 v133, 0xbfb8aa3b, v191
	v_exp_f32_e32 v132, v132
	v_exp_f32_e32 v133, v133
	v_lshlrev_b32_e32 v164, 16, v134
	v_and_b32_e32 v165, 0xffff0000, v134
	v_add_f32_e32 v132, 1.0, v132
	v_add_f32_e32 v133, 1.0, v133
	v_rcp_f32_e32 v132, v132
	v_rcp_f32_e32 v133, v133
	v_lshlrev_b32_e32 v134, 16, v135
	v_and_b32_e32 v135, 0xffff0000, v135
	global_store_dwordx4 v[172:173], v[182:185], off sc1
	s_nop 1
	v_pk_fma_f32 v[128:129], v[132:133], v[164:165], v[128:129]
	v_mul_f32_e32 v132, 0xbfb8aa3b, v188
	v_mul_f32_e32 v133, 0xbfb8aa3b, v189
	v_exp_f32_e32 v132, v132
	v_exp_f32_e32 v133, v133
	v_lshl_add_u64 v[164:165], v[154:155], 0, s[16:17]
	v_add_f32_e32 v132, 1.0, v132
	v_add_f32_e32 v133, 1.0, v133
	v_rcp_f32_e32 v132, v132
	v_rcp_f32_e32 v133, v133
	s_nop 0
	v_pk_fma_f32 v[130:131], v[132:133], v[134:135], v[130:131]
	s_nop 0
	global_store_dwordx4 v[166:167], v[128:131], off sc1
	s_nop 1
	v_cvt_pk_bf16_f32 v132, v182, v183
	v_cvt_pk_bf16_f32 v133, v184, v185
	v_cvt_pk_bf16_f32 v134, v128, v129
	v_cvt_pk_bf16_f32 v135, v130, v131
	v_pk_mul_f32 v[128:129], v[128:129], v[128:129]
	global_store_dwordx4 v[164:165], v[132:135], off sc1
	s_nop 1
	v_pk_mul_f32 v[132:133], v[182:183], v[182:183]
	v_pk_mul_f32 v[134:135], v[184:185], v[184:185]
	v_add_f32_e32 v132, v132, v133
	v_add_f32_e32 v134, v134, v135
	v_pk_mul_f32 v[130:131], v[130:131], v[130:131]
	v_add_f32_e32 v132, v132, v134
	v_add_f32_e32 v128, v128, v129
	v_add_f32_e32 v128, v128, v132
	v_add_f32_e32 v129, v130, v131
	v_add_f32_e32 v128, v129, v128
	v_add_f32_e32 v128, v136, v128
	ds_bpermute_b32 v129, v177, v128
	s_waitcnt lgkmcnt(0)
	v_add_f32_e32 v128, v128, v129
	ds_bpermute_b32 v129, v178, v128
	s_and_saveexec_b64 s[16:17], s[6:7]
	s_cbranch_execz .LBB0_725
	v_lshl_add_u64 v[130:131], v[162:163], 2, s[60:61]
	s_waitcnt lgkmcnt(0)
	v_add_f32_e32 v128, v128, v129
	global_atomic_add_f32 v[130:131], v128, off
; __device__ __forceinline__ unsigned cvt_pk_bf16(float lo, float hi) { unsigned r; asm volatile("v_cvt_pk_bf16_f32 %0, %1, %2" : "=v"(r) : "v"(lo), "v"(hi)); return r; }
; template <bool WT> __device__ __forceinline__ void st16(void* p, f32x4 v) { if constexpr (WT) st16_wt(p, v); else *(f32x4*)p = v; }
; __device__ __forceinline__ float rstd_of(float ss) { return __builtin_amdgcn_rsqf(ss * (1.0f / 2048.0f) + NORM_EPS); }
;     __device__ __forceinline__ void operator()(const f32x4 (&acc)[2][2][4][2], const Unit& u, int wr, int wc, int fr, int fq) const {
;     ...
;             for (int m = 0; m < 4; ++m) { const size_t ro = (size_t)(ai * HALF + m * 16) * LD; float sq = 0.f; const int grow = u.pm * BM + ai * HALF + m * 16 + rt; const float rs = rstd_of(ssin[grow]);
; #pragma unroll
;                 for (int bj = 0; bj < 2; ++bj) { const size_t o = obase + ro + bj * HALF; const f32x4 h0 = *(const f32x4*)(H + o), h1 = *(const f32x4*)(H + o + 4); const u32x4 ev = *(const u32x4*)(E + o);
;                     const f32x4 a0 = acc[ai][bj][m][0] * rs, a1 = acc[ai][bj][m][1] * rs; f32x4 v0, v1;
;                     v0[0] = h0[0] + sigmoid_f(a0[0]) * __uint_as_float(ev.x << 16); v0[1] = h0[1] + sigmoid_f(a0[1]) * __uint_as_float(ev.x & 0xffff0000u);
;                     v0[2] = h0[2] + sigmoid_f(a0[2]) * __uint_as_float(ev.y << 16); v0[3] = h0[3] + sigmoid_f(a0[3]) * __uint_as_float(ev.y & 0xffff0000u);
;                     v1[0] = h1[0] + sigmoid_f(a1[0]) * __uint_as_float(ev.z << 16); v1[1] = h1[1] + sigmoid_f(a1[1]) * __uint_as_float(ev.z & 0xffff0000u);
;                     v1[2] = h1[2] + sigmoid_f(a1[2]) * __uint_as_float(ev.w << 16); v1[3] = h1[3] + sigmoid_f(a1[3]) * __uint_as_float(ev.w & 0xffff0000u);
;                     st16<WT>(H + o, v0); st16<WT>(H + o + 4, v1);
;                     if constexpr (WXB) { u32x4 w; w.x = cvt_pk_bf16(v0[0], v0[1]); w.y = cvt_pk_bf16(v0[2], v0[3]); w.z = cvt_pk_bf16(v1[0], v1[1]); w.w = cvt_pk_bf16(v1[2], v1[3]);
;                         st16<WT>(XB + o, __builtin_bit_cast(f32x4, w)); }
;                     sq += (v0[0] * v0[0] + v0[1] * v0[1]) + (v0[2] * v0[2] + v0[3] * v0[3]) + (v1[0] * v1[0] + v1[1] * v1[1]) + (v1[2] * v1[2] + v1[3] * v1[3]); }
;                 sq += __shfl_xor(sq, 16); sq += __shfl_xor(sq, 32);
;                 if (fq == 0) ss_add<false>(ssout + grow, sq);
.LBB0_725:
	s_or_b64 exec, exec, s[16:17]
	v_or_b32_e32 v162, 48, v160
	v_ashrrev_i32_e32 v163, 31, v162
	s_waitcnt lgkmcnt(0)
	v_add_co_u32_e32 v166, vcc, 0x60000, v156
	s_mov_b64 s[16:17], 0x60000
	s_nop 0
	v_addc_co_u32_e32 v167, vcc, 0, v157, vcc
	v_add_co_u32_e32 v164, vcc, 0x30000, v158
	v_lshl_add_u64 v[168:169], v[156:157], 0, s[16:17]
	s_nop 0
	v_addc_co_u32_e32 v165, vcc, 0, v159, vcc
	s_mov_b64 s[16:17], 0x60010
	v_lshl_add_u64 v[170:171], v[156:157], 0, s[16:17]
	s_mov_b64 s[16:17], 0x30000
	v_fmamk_f32 v128, v251, 0x3a000000, v181
	v_add_u32_e32 v254, 0x80, v160
	v_ashrrev_i32_e32 v255, 31, v254
	v_lshl_add_u64 v[252:253], v[254:255], 2, s[58:59]
	global_load_dword v251, v[252:253], off
	v_rsq_f32_e32 v146, v128
	global_load_dwordx4 v[128:131], v[166:167], off
	global_load_dwordx4 v[132:135], v[168:169], off offset:16
	global_load_dwordx4 v[136:139], v[164:165], off
	v_pk_mul_f32 v[172:173], v[102:103], v[146:147] op_sel_hi:[1,0]
	v_pk_mul_f32 v[186:187], v[96:97], v[146:147] op_sel_hi:[1,0]
	v_pk_mul_f32 v[182:183], v[100:101], v[146:147] op_sel_hi:[1,0]
	v_pk_mul_f32 v[184:185], v[98:99], v[146:147] op_sel_hi:[1,0]
	v_mul_f32_e32 v161, 0xbfb8aa3b, v182
	v_exp_f32_e32 v161, v161
	v_pk_mul_f32 v[190:191], v[64:65], v[146:147] op_sel_hi:[1,0]
	v_add_f32_e32 v161, 1.0, v161
	v_rcp_f32_e32 v182, v161
	v_mul_f32_e32 v161, 0xbfb8aa3b, v183
	v_exp_f32_e32 v161, v161
	s_waitcnt vmcnt(0)
	v_lshlrev_b32_e32 v188, 16, v136
	v_and_b32_e32 v189, 0xffff0000, v136
	v_mul_f32_e32 v136, 0xbfb8aa3b, v172
	v_exp_f32_e32 v136, v136
	v_add_f32_e32 v161, 1.0, v161
	v_rcp_f32_e32 v183, v161
	v_add_f32_e32 v136, 1.0, v136
	v_rcp_f32_e32 v172, v136
	v_mul_f32_e32 v136, 0xbfb8aa3b, v173
	v_exp_f32_e32 v136, v136
	v_pk_fma_f32 v[128:129], v[182:183], v[188:189], v[128:129]
	v_pk_mul_f32 v[188:189], v[66:67], v[146:147] op_sel_hi:[1,0]
	v_add_f32_e32 v136, 1.0, v136
	v_rcp_f32_e32 v173, v136
	v_lshlrev_b32_e32 v136, 16, v137
	v_and_b32_e32 v137, 0xffff0000, v137
	v_pk_fma_f32 v[130:131], v[172:173], v[136:137], v[130:131]
	v_mul_f32_e32 v136, 0xbfb8aa3b, v186
	v_mul_f32_e32 v137, 0xbfb8aa3b, v187
	v_exp_f32_e32 v136, v136
	v_exp_f32_e32 v137, v137
	v_lshlrev_b32_e32 v172, 16, v138
	v_and_b32_e32 v173, 0xffff0000, v138
	v_add_f32_e32 v136, 1.0, v136
	v_add_f32_e32 v137, 1.0, v137
	v_rcp_f32_e32 v136, v136
	v_rcp_f32_e32 v137, v137
	v_lshlrev_b32_e32 v138, 16, v139
	v_and_b32_e32 v139, 0xffff0000, v139
	global_store_dwordx4 v[168:169], v[128:131], off sc1
	s_nop 1
	v_pk_fma_f32 v[132:133], v[136:137], v[172:173], v[132:133]
	v_mul_f32_e32 v136, 0xbfb8aa3b, v184
	v_mul_f32_e32 v137, 0xbfb8aa3b, v185
	v_exp_f32_e32 v136, v136
	v_exp_f32_e32 v137, v137
	v_lshl_add_u64 v[168:169], v[154:155], 0, s[16:17]
	s_mov_b64 s[16:17], 0x60200
	v_add_f32_e32 v136, 1.0, v136
	v_add_f32_e32 v137, 1.0, v137
	v_rcp_f32_e32 v136, v136
	v_rcp_f32_e32 v137, v137
	v_lshl_add_u64 v[172:173], v[156:157], 0, s[16:17]
	v_pk_mul_f32 v[186:187], v[68:69], v[146:147] op_sel_hi:[1,0]
	s_mov_b64 s[16:17], 0x60210
	v_pk_fma_f32 v[134:135], v[136:137], v[138:139], v[134:135]
	s_nop 0
	global_store_dwordx4 v[170:171], v[132:135], off sc1
	s_nop 1
	v_cvt_pk_bf16_f32 v136, v128, v129
	v_cvt_pk_bf16_f32 v137, v130, v131
	v_cvt_pk_bf16_f32 v138, v132, v133
	v_cvt_pk_bf16_f32 v139, v134, v135
	v_pk_mul_f32 v[170:171], v[130:131], v[130:131]
	global_store_dwordx4 v[168:169], v[136:139], off sc1
	s_nop 1
	v_pk_mul_f32 v[168:169], v[128:129], v[128:129]
	v_pk_mul_f32 v[138:139], v[132:133], v[132:133]
	v_pk_mul_f32 v[136:137], v[134:135], v[134:135]
	global_load_dwordx4 v[182:185], v[166:167], off offset:512
	global_load_dwordx4 v[128:131], v[172:173], off offset:16
	global_load_dwordx4 v[132:135], v[164:165], off offset:256
	v_pk_mul_f32 v[164:165], v[70:71], v[146:147] op_sel_hi:[1,0]
	v_mul_f32_e32 v146, 0xbfb8aa3b, v186
	v_exp_f32_e32 v146, v146
	v_lshl_add_u64 v[166:167], v[156:157], 0, s[16:17]
	s_mov_b64 s[16:17], 0x30100
	v_add_f32_e32 v161, v168, v169
	v_add_f32_e32 v146, 1.0, v146
	v_rcp_f32_e32 v186, v146
	v_mul_f32_e32 v146, 0xbfb8aa3b, v187
	v_exp_f32_e32 v146, v146
	v_add_f32_e32 v138, v138, v139
	v_add_f32_e32 v136, v136, v137
	v_add_f32_e32 v146, 1.0, v146
	v_rcp_f32_e32 v187, v146
	v_add_f32_e32 v146, v170, v171
	v_add_f32_e32 v146, v161, v146
	v_add_f32_e32 v138, v138, v146
	v_add_f32_e32 v136, v136, v138
	s_waitcnt vmcnt(0)
	v_lshlrev_b32_e32 v192, 16, v132
	v_and_b32_e32 v193, 0xffff0000, v132
	v_mul_f32_e32 v132, 0xbfb8aa3b, v164
	v_exp_f32_e32 v132, v132
	v_pk_fma_f32 v[182:183], v[186:187], v[192:193], v[182:183]
	v_add_f32_e32 v132, 1.0, v132
	v_rcp_f32_e32 v164, v132
	v_mul_f32_e32 v132, 0xbfb8aa3b, v165
	v_exp_f32_e32 v132, v132
	s_nop 0
	v_add_f32_e32 v132, 1.0, v132
	v_rcp_f32_e32 v165, v132
	v_lshlrev_b32_e32 v132, 16, v133
	v_and_b32_e32 v133, 0xffff0000, v133
	v_pk_fma_f32 v[184:185], v[164:165], v[132:133], v[184:185]
	v_mul_f32_e32 v132, 0xbfb8aa3b, v190
	v_mul_f32_e32 v133, 0xbfb8aa3b, v191
	v_exp_f32_e32 v132, v132
	v_exp_f32_e32 v133, v133
	v_lshlrev_b32_e32 v164, 16, v134
	v_and_b32_e32 v165, 0xffff0000, v134
	v_add_f32_e32 v132, 1.0, v132
	v_add_f32_e32 v133, 1.0, v133
	v_rcp_f32_e32 v132, v132
	v_rcp_f32_e32 v133, v133
	v_lshlrev_b32_e32 v134, 16, v135
	v_and_b32_e32 v135, 0xffff0000, v135
	global_store_dwordx4 v[172:173], v[182:185], off sc1
	s_nop 1
	v_pk_fma_f32 v[128:129], v[132:133], v[164:165], v[128:129]
	v_mul_f32_e32 v132, 0xbfb8aa3b, v188
	v_mul_f32_e32 v133, 0xbfb8aa3b, v189
	v_exp_f32_e32 v132, v132
	v_exp_f32_e32 v133, v133
	v_lshl_add_u64 v[164:165], v[154:155], 0, s[16:17]
	v_add_f32_e32 v132, 1.0, v132
	v_add_f32_e32 v133, 1.0, v133
	v_rcp_f32_e32 v132, v132
	v_rcp_f32_e32 v133, v133
	s_nop 0
	v_pk_fma_f32 v[130:131], v[132:133], v[134:135], v[130:131]
	s_nop 0
	global_store_dwordx4 v[166:167], v[128:131], off sc1
	s_nop 1
	v_cvt_pk_bf16_f32 v132, v182, v183
	v_cvt_pk_bf16_f32 v133, v184, v185
	v_cvt_pk_bf16_f32 v134, v128, v129
	v_cvt_pk_bf16_f32 v135, v130, v131
	v_pk_mul_f32 v[128:129], v[128:129], v[128:129]
	global_store_dwordx4 v[164:165], v[132:135], off sc1
	s_nop 1
	v_pk_mul_f32 v[132:133], v[182:183], v[182:183]
	v_pk_mul_f32 v[134:135], v[184:185], v[184:185]
	v_add_f32_e32 v132, v132, v133
	v_add_f32_e32 v134, v134, v135
	v_pk_mul_f32 v[130:131], v[130:131], v[130:131]
	v_add_f32_e32 v132, v132, v134
	v_add_f32_e32 v128, v128, v129
	v_add_f32_e32 v128, v128, v132
	v_add_f32_e32 v129, v130, v131
	v_add_f32_e32 v128, v129, v128
	v_add_f32_e32 v128, v136, v128
	ds_bpermute_b32 v129, v177, v128
	s_waitcnt lgkmcnt(0)
	v_add_f32_e32 v128, v128, v129
	ds_bpermute_b32 v129, v178, v128
	s_and_saveexec_b64 s[16:17], s[6:7]
	s_cbranch_execz .LBB0_727
	v_lshl_add_u64 v[130:131], v[162:163], 2, s[60:61]
	s_waitcnt lgkmcnt(0)
	v_add_f32_e32 v128, v128, v129
	global_atomic_add_f32 v[130:131], v128, off
; __device__ __forceinline__ unsigned cvt_pk_bf16(float lo, float hi) { unsigned r; asm volatile("v_cvt_pk_bf16_f32 %0, %1, %2" : "=v"(r) : "v"(lo), "v"(hi)); return r; }
; template <bool WT> __device__ __forceinline__ void st16(void* p, f32x4 v) { if constexpr (WT) st16_wt(p, v); else *(f32x4*)p = v; }
; __device__ __forceinline__ float rstd_of(float ss) { return __builtin_amdgcn_rsqf(ss * (1.0f / 2048.0f) + NORM_EPS); }
;     __device__ __forceinline__ void operator()(const f32x4 (&acc)[2][2][4][2], const Unit& u, int wr, int wc, int fr, int fq) const {
;     ...
;             for (int m = 0; m < 4; ++m) { const size_t ro = (size_t)(ai * HALF + m * 16) * LD; float sq = 0.f; const int grow = u.pm * BM + ai * HALF + m * 16 + rt; const float rs = rstd_of(ssin[grow]);
; #pragma unroll
;                 for (int bj = 0; bj < 2; ++bj) { const size_t o = obase + ro + bj * HALF; const f32x4 h0 = *(const f32x4*)(H + o), h1 = *(const f32x4*)(H + o + 4); const u32x4 ev = *(const u32x4*)(E + o);
;                     const f32x4 a0 = acc[ai][bj][m][0] * rs, a1 = acc[ai][bj][m][1] * rs; f32x4 v0, v1;
;                     v0[0] = h0[0] + sigmoid_f(a0[0]) * __uint_as_float(ev.x << 16); v0[1] = h0[1] + sigmoid_f(a0[1]) * __uint_as_float(ev.x & 0xffff0000u);
;                     v0[2] = h0[2] + sigmoid_f(a0[2]) * __uint_as_float(ev.y << 16); v0[3] = h0[3] + sigmoid_f(a0[3]) * __uint_as_float(ev.y & 0xffff0000u);
;                     v1[0] = h1[0] + sigmoid_f(a1[0]) * __uint_as_float(ev.z << 16); v1[1] = h1[1] + sigmoid_f(a1[1]) * __uint_as_float(ev.z & 0xffff0000u);
;                     v1[2] = h1[2] + sigmoid_f(a1[2]) * __uint_as_float(ev.w << 16); v1[3] = h1[3] + sigmoid_f(a1[3]) * __uint_as_float(ev.w & 0xffff0000u);
;                     st16<WT>(H + o, v0); st16<WT>(H + o + 4, v1);
;                     if constexpr (WXB) { u32x4 w; w.x = cvt_pk_bf16(v0[0], v0[1]); w.y = cvt_pk_bf16(v0[2], v0[3]); w.z = cvt_pk_bf16(v1[0], v1[1]); w.w = cvt_pk_bf16(v1[2], v1[3]);
;                         st16<WT>(XB + o, __builtin_bit_cast(f32x4, w)); }
;                     sq += (v0[0] * v0[0] + v0[1] * v0[1]) + (v0[2] * v0[2] + v0[3] * v0[3]) + (v1[0] * v1[0] + v1[1] * v1[1]) + (v1[2] * v1[2] + v1[3] * v1[3]); }
;                 sq += __shfl_xor(sq, 16); sq += __shfl_xor(sq, 32);
;                 if (fq == 0) ss_add<false>(ssout + grow, sq);
.LBB0_727:
	s_or_b64 exec, exec, s[16:17]
	v_add_u32_e32 v160, 0x80, v160
	v_ashrrev_i32_e32 v161, 31, v160
	s_waitcnt lgkmcnt(0)
	v_add_co_u32_e32 v164, vcc, 0x100000, v156
	s_mov_b64 s[16:17], 0x100000
	s_nop 0
	v_addc_co_u32_e32 v165, vcc, 0, v157, vcc
	v_add_co_u32_e32 v162, vcc, 0x80000, v158
	v_lshl_add_u64 v[166:167], v[156:157], 0, s[16:17]
	s_nop 0
	v_addc_co_u32_e32 v163, vcc, 0, v159, vcc
	s_mov_b64 s[16:17], 0x100010
	v_lshl_add_u64 v[168:169], v[156:157], 0, s[16:17]
	s_mov_b64 s[16:17], 0x80000
	v_fmamk_f32 v128, v251, 0x3a000000, v181
	v_or_b32_e32 v254, 16, v160
	v_ashrrev_i32_e32 v255, 31, v254
	v_lshl_add_u64 v[252:253], v[254:255], 2, s[58:59]
	global_load_dword v251, v[252:253], off
	v_rsq_f32_e32 v146, v128
	global_load_dwordx4 v[128:131], v[164:165], off
	global_load_dwordx4 v[132:135], v[166:167], off offset:16
	global_load_dwordx4 v[136:139], v[162:163], off
	v_pk_mul_f32 v[170:171], v[62:63], v[146:147] op_sel_hi:[1,0]
	v_pk_mul_f32 v[184:185], v[56:57], v[146:147] op_sel_hi:[1,0]
	v_pk_mul_f32 v[172:173], v[60:61], v[146:147] op_sel_hi:[1,0]
	v_pk_mul_f32 v[182:183], v[58:59], v[146:147] op_sel_hi:[1,0]
	v_mul_f32_e32 v172, 0xbfb8aa3b, v172
	v_mul_f32_e32 v173, 0xbfb8aa3b, v173
	v_exp_f32_e32 v172, v172
	v_exp_f32_e32 v173, v173
	v_pk_mul_f32 v[188:189], v[24:25], v[146:147] op_sel_hi:[1,0]
	v_add_f32_e32 v172, 1.0, v172
	v_add_f32_e32 v173, 1.0, v173
	v_rcp_f32_e32 v172, v172
	v_rcp_f32_e32 v173, v173
	s_waitcnt vmcnt(0)
	v_lshlrev_b32_e32 v186, 16, v136
	v_and_b32_e32 v187, 0xffff0000, v136
	v_mul_f32_e32 v136, 0xbfb8aa3b, v170
	v_exp_f32_e32 v136, v136
	v_pk_fma_f32 v[128:129], v[172:173], v[186:187], v[128:129]
	v_pk_mul_f32 v[172:173], v[28:29], v[146:147] op_sel_hi:[1,0]
	v_pk_mul_f32 v[186:187], v[26:27], v[146:147] op_sel_hi:[1,0]
	v_add_f32_e32 v136, 1.0, v136
	v_rcp_f32_e32 v170, v136
	v_mul_f32_e32 v136, 0xbfb8aa3b, v171
	v_exp_f32_e32 v136, v136
	s_nop 0
	v_add_f32_e32 v136, 1.0, v136
	v_rcp_f32_e32 v171, v136
	v_lshlrev_b32_e32 v136, 16, v137
	v_and_b32_e32 v137, 0xffff0000, v137
	v_pk_fma_f32 v[130:131], v[170:171], v[136:137], v[130:131]
	v_mul_f32_e32 v136, 0xbfb8aa3b, v184
	v_mul_f32_e32 v137, 0xbfb8aa3b, v185
	v_exp_f32_e32 v136, v136
	v_exp_f32_e32 v137, v137
	v_lshlrev_b32_e32 v170, 16, v138
	v_and_b32_e32 v171, 0xffff0000, v138
	v_add_f32_e32 v136, 1.0, v136
	v_add_f32_e32 v137, 1.0, v137
	v_rcp_f32_e32 v136, v136
	v_rcp_f32_e32 v137, v137
	v_lshlrev_b32_e32 v138, 16, v139
	v_and_b32_e32 v139, 0xffff0000, v139
	global_store_dwordx4 v[166:167], v[128:131], off sc1
	s_nop 1
	v_pk_fma_f32 v[132:133], v[136:137], v[170:171], v[132:133]
	v_mul_f32_e32 v136, 0xbfb8aa3b, v182
	v_mul_f32_e32 v137, 0xbfb8aa3b, v183
	v_exp_f32_e32 v136, v136
	v_exp_f32_e32 v137, v137
	v_lshl_add_u64 v[166:167], v[154:155], 0, s[16:17]
	s_mov_b64 s[16:17], 0x100200
	v_add_f32_e32 v136, 1.0, v136
	v_add_f32_e32 v137, 1.0, v137
	v_rcp_f32_e32 v136, v136
	v_rcp_f32_e32 v137, v137
	v_lshl_add_u64 v[170:171], v[156:157], 0, s[16:17]
	s_mov_b64 s[16:17], 0x100210
	v_pk_fma_f32 v[134:135], v[136:137], v[138:139], v[134:135]
	s_nop 0
	global_store_dwordx4 v[168:169], v[132:135], off sc1
	s_nop 1
	v_cvt_pk_bf16_f32 v136, v128, v129
	v_cvt_pk_bf16_f32 v137, v130, v131
	v_cvt_pk_bf16_f32 v138, v132, v133
	v_cvt_pk_bf16_f32 v139, v134, v135
	v_pk_mul_f32 v[168:169], v[130:131], v[130:131]
	global_store_dwordx4 v[166:167], v[136:139], off sc1
	s_nop 1
	v_pk_mul_f32 v[166:167], v[128:129], v[128:129]
	v_pk_mul_f32 v[138:139], v[132:133], v[132:133]
	v_pk_mul_f32 v[136:137], v[134:135], v[134:135]
	global_load_dwordx4 v[182:185], v[164:165], off offset:512
	global_load_dwordx4 v[128:131], v[170:171], off offset:16
	global_load_dwordx4 v[132:135], v[162:163], off offset:256
	v_pk_mul_f32 v[162:163], v[30:31], v[146:147] op_sel_hi:[1,0]
	v_mul_f32_e32 v146, 0xbfb8aa3b, v172
	v_exp_f32_e32 v146, v146
	v_lshl_add_u64 v[164:165], v[156:157], 0, s[16:17]
	s_mov_b64 s[16:17], 0x80100
	v_add_f32_e32 v138, v138, v139
	v_add_f32_e32 v146, 1.0, v146
	v_rcp_f32_e32 v172, v146
	v_mul_f32_e32 v146, 0xbfb8aa3b, v173
	v_exp_f32_e32 v146, v146
	v_add_f32_e32 v136, v136, v137
	v_add_f32_e32 v146, 1.0, v146
	v_rcp_f32_e32 v173, v146
	v_add_f32_e32 v146, v168, v169
	s_waitcnt vmcnt(0)
	v_lshlrev_b32_e32 v190, 16, v132
	v_and_b32_e32 v191, 0xffff0000, v132
	v_mul_f32_e32 v132, 0xbfb8aa3b, v162
	v_exp_f32_e32 v132, v132
	v_pk_fma_f32 v[182:183], v[172:173], v[190:191], v[182:183]
	v_add_f32_e32 v132, 1.0, v132
	v_rcp_f32_e32 v162, v132
	v_mul_f32_e32 v132, 0xbfb8aa3b, v163
	v_exp_f32_e32 v132, v132
	s_nop 0
	v_add_f32_e32 v132, 1.0, v132
	v_rcp_f32_e32 v163, v132
	v_lshlrev_b32_e32 v132, 16, v133
	v_and_b32_e32 v133, 0xffff0000, v133
	v_pk_fma_f32 v[184:185], v[162:163], v[132:133], v[184:185]
	v_mul_f32_e32 v132, 0xbfb8aa3b, v188
	v_mul_f32_e32 v133, 0xbfb8aa3b, v189
	v_exp_f32_e32 v132, v132
	v_exp_f32_e32 v133, v133
	v_lshlrev_b32_e32 v162, 16, v134
	v_and_b32_e32 v163, 0xffff0000, v134
	v_add_f32_e32 v132, 1.0, v132
	v_add_f32_e32 v133, 1.0, v133
	v_rcp_f32_e32 v132, v132
	v_rcp_f32_e32 v133, v133
	v_lshlrev_b32_e32 v134, 16, v135
	v_and_b32_e32 v135, 0xffff0000, v135
	global_store_dwordx4 v[170:171], v[182:185], off sc1
	s_nop 1
	v_pk_fma_f32 v[128:129], v[132:133], v[162:163], v[128:129]
	v_mul_f32_e32 v132, 0xbfb8aa3b, v186
	v_mul_f32_e32 v133, 0xbfb8aa3b, v187
	v_exp_f32_e32 v132, v132
	v_exp_f32_e32 v133, v133
	v_lshl_add_u64 v[162:163], v[154:155], 0, s[16:17]
	v_add_f32_e32 v132, 1.0, v132
	v_add_f32_e32 v133, 1.0, v133
	v_rcp_f32_e32 v132, v132
	v_rcp_f32_e32 v133, v133
	s_nop 0
	v_pk_fma_f32 v[130:131], v[132:133], v[134:135], v[130:131]
	s_nop 0
	global_store_dwordx4 v[164:165], v[128:131], off sc1
	s_nop 1
	v_cvt_pk_bf16_f32 v132, v182, v183
	v_cvt_pk_bf16_f32 v133, v184, v185
	v_cvt_pk_bf16_f32 v134, v128, v129
	v_cvt_pk_bf16_f32 v135, v130, v131
	v_pk_mul_f32 v[128:129], v[128:129], v[128:129]
	global_store_dwordx4 v[162:163], v[132:135], off sc1
	s_nop 1
	v_pk_mul_f32 v[132:133], v[182:183], v[182:183]
	v_pk_mul_f32 v[134:135], v[184:185], v[184:185]
	v_add_f32_e32 v162, v166, v167
	v_add_f32_e32 v134, v134, v135
	v_add_f32_e32 v132, v132, v133
	v_pk_mul_f32 v[130:131], v[130:131], v[130:131]
	v_add_f32_e32 v146, v162, v146
	v_add_f32_e32 v132, v132, v134
	v_add_f32_e32 v128, v128, v129
	v_add_f32_e32 v138, v138, v146
	v_add_f32_e32 v128, v128, v132
	v_add_f32_e32 v129, v130, v131
	v_add_f32_e32 v136, v136, v138
	v_add_f32_e32 v128, v129, v128
	v_add_f32_e32 v128, v136, v128
	ds_bpermute_b32 v129, v177, v128
	s_waitcnt lgkmcnt(0)
	v_add_f32_e32 v128, v128, v129
	ds_bpermute_b32 v129, v178, v128
	s_and_saveexec_b64 s[16:17], s[6:7]
	s_cbranch_execz .LBB0_729
	v_lshl_add_u64 v[130:131], v[160:161], 2, s[60:61]
	s_waitcnt lgkmcnt(0)
	v_add_f32_e32 v128, v128, v129
	global_atomic_add_f32 v[130:131], v128, off
; __device__ __forceinline__ unsigned cvt_pk_bf16(float lo, float hi) { unsigned r; asm volatile("v_cvt_pk_bf16_f32 %0, %1, %2" : "=v"(r) : "v"(lo), "v"(hi)); return r; }
; template <bool WT> __device__ __forceinline__ void st16(void* p, f32x4 v) { if constexpr (WT) st16_wt(p, v); else *(f32x4*)p = v; }
; __device__ __forceinline__ float rstd_of(float ss) { return __builtin_amdgcn_rsqf(ss * (1.0f / 2048.0f) + NORM_EPS); }
;     __device__ __forceinline__ void operator()(const f32x4 (&acc)[2][2][4][2], const Unit& u, int wr, int wc, int fr, int fq) const {
;     ...
;             for (int m = 0; m < 4; ++m) { const size_t ro = (size_t)(ai * HALF + m * 16) * LD; float sq = 0.f; const int grow = u.pm * BM + ai * HALF + m * 16 + rt; const float rs = rstd_of(ssin[grow]);
; #pragma unroll
;                 for (int bj = 0; bj < 2; ++bj) { const size_t o = obase + ro + bj * HALF; const f32x4 h0 = *(const f32x4*)(H + o), h1 = *(const f32x4*)(H + o + 4); const u32x4 ev = *(const u32x4*)(E + o);
;                     const f32x4 a0 = acc[ai][bj][m][0] * rs, a1 = acc[ai][bj][m][1] * rs; f32x4 v0, v1;
;                     v0[0] = h0[0] + sigmoid_f(a0[0]) * __uint_as_float(ev.x << 16); v0[1] = h0[1] + sigmoid_f(a0[1]) * __uint_as_float(ev.x & 0xffff0000u);
;                     v0[2] = h0[2] + sigmoid_f(a0[2]) * __uint_as_float(ev.y << 16); v0[3] = h0[3] + sigmoid_f(a0[3]) * __uint_as_float(ev.y & 0xffff0000u);
;                     v1[0] = h1[0] + sigmoid_f(a1[0]) * __uint_as_float(ev.z << 16); v1[1] = h1[1] + sigmoid_f(a1[1]) * __uint_as_float(ev.z & 0xffff0000u);
;                     v1[2] = h1[2] + sigmoid_f(a1[2]) * __uint_as_float(ev.w << 16); v1[3] = h1[3] + sigmoid_f(a1[3]) * __uint_as_float(ev.w & 0xffff0000u);
;                     st16<WT>(H + o, v0); st16<WT>(H + o + 4, v1);
;                     if constexpr (WXB) { u32x4 w; w.x = cvt_pk_bf16(v0[0], v0[1]); w.y = cvt_pk_bf16(v0[2], v0[3]); w.z = cvt_pk_bf16(v1[0], v1[1]); w.w = cvt_pk_bf16(v1[2], v1[3]);
;                         st16<WT>(XB + o, __builtin_bit_cast(f32x4, w)); }
;                     sq += (v0[0] * v0[0] + v0[1] * v0[1]) + (v0[2] * v0[2] + v0[3] * v0[3]) + (v1[0] * v1[0] + v1[1] * v1[1]) + (v1[2] * v1[2] + v1[3] * v1[3]); }
;                 sq += __shfl_xor(sq, 16); sq += __shfl_xor(sq, 32);
;                 if (fq == 0) ss_add<false>(ssout + grow, sq);
.LBB0_729:
	s_or_b64 exec, exec, s[16:17]
	v_or_b32_e32 v162, 16, v160
	v_ashrrev_i32_e32 v163, 31, v162
	s_waitcnt lgkmcnt(0)
	v_add_co_u32_e32 v166, vcc, 0x120000, v156
	s_mov_b64 s[16:17], 0x120000
	s_nop 0
	v_addc_co_u32_e32 v167, vcc, 0, v157, vcc
	v_add_co_u32_e32 v164, vcc, 0x90000, v158
	v_lshl_add_u64 v[168:169], v[156:157], 0, s[16:17]
	s_nop 0
	v_addc_co_u32_e32 v165, vcc, 0, v159, vcc
	s_mov_b64 s[16:17], 0x120010
	v_lshl_add_u64 v[170:171], v[156:157], 0, s[16:17]
	s_mov_b64 s[16:17], 0x90000
	v_fmamk_f32 v128, v251, 0x3a000000, v181
	v_or_b32_e32 v254, 32, v160
	v_ashrrev_i32_e32 v255, 31, v254
	v_lshl_add_u64 v[252:253], v[254:255], 2, s[58:59]
	global_load_dword v251, v[252:253], off
	v_rsq_f32_e32 v146, v128
	global_load_dwordx4 v[128:131], v[166:167], off
	global_load_dwordx4 v[132:135], v[168:169], off offset:16
	global_load_dwordx4 v[136:139], v[164:165], off
	v_pk_mul_f32 v[172:173], v[54:55], v[146:147] op_sel_hi:[1,0]
	v_pk_mul_f32 v[186:187], v[48:49], v[146:147] op_sel_hi:[1,0]
	v_pk_mul_f32 v[182:183], v[52:53], v[146:147] op_sel_hi:[1,0]
	v_pk_mul_f32 v[184:185], v[50:51], v[146:147] op_sel_hi:[1,0]
	v_mul_f32_e32 v161, 0xbfb8aa3b, v182
	v_exp_f32_e32 v161, v161
	v_pk_mul_f32 v[190:191], v[16:17], v[146:147] op_sel_hi:[1,0]
	v_add_f32_e32 v161, 1.0, v161
	v_rcp_f32_e32 v182, v161
	v_mul_f32_e32 v161, 0xbfb8aa3b, v183
	v_exp_f32_e32 v161, v161
	s_waitcnt vmcnt(0)
	v_lshlrev_b32_e32 v188, 16, v136
	v_and_b32_e32 v189, 0xffff0000, v136
	v_mul_f32_e32 v136, 0xbfb8aa3b, v172
	v_exp_f32_e32 v136, v136
	v_add_f32_e32 v161, 1.0, v161
	v_rcp_f32_e32 v183, v161
	v_add_f32_e32 v136, 1.0, v136
	v_rcp_f32_e32 v172, v136
	v_mul_f32_e32 v136, 0xbfb8aa3b, v173
	v_exp_f32_e32 v136, v136
	v_pk_fma_f32 v[128:129], v[182:183], v[188:189], v[128:129]
	v_pk_mul_f32 v[188:189], v[18:19], v[146:147] op_sel_hi:[1,0]
	v_add_f32_e32 v136, 1.0, v136
	v_rcp_f32_e32 v173, v136
	v_lshlrev_b32_e32 v136, 16, v137
	v_and_b32_e32 v137, 0xffff0000, v137
	v_pk_fma_f32 v[130:131], v[172:173], v[136:137], v[130:131]
	v_mul_f32_e32 v136, 0xbfb8aa3b, v186
	v_mul_f32_e32 v137, 0xbfb8aa3b, v187
	v_exp_f32_e32 v136, v136
	v_exp_f32_e32 v137, v137
	v_lshlrev_b32_e32 v172, 16, v138
	v_and_b32_e32 v173, 0xffff0000, v138
	v_add_f32_e32 v136, 1.0, v136
	v_add_f32_e32 v137, 1.0, v137
	v_rcp_f32_e32 v136, v136
	v_rcp_f32_e32 v137, v137
	v_lshlrev_b32_e32 v138, 16, v139
	v_and_b32_e32 v139, 0xffff0000, v139
	global_store_dwordx4 v[168:169], v[128:131], off sc1
	s_nop 1
	v_pk_fma_f32 v[132:133], v[136:137], v[172:173], v[132:133]
	v_mul_f32_e32 v136, 0xbfb8aa3b, v184
	v_mul_f32_e32 v137, 0xbfb8aa3b, v185
	v_exp_f32_e32 v136, v136
	v_exp_f32_e32 v137, v137
	v_lshl_add_u64 v[168:169], v[154:155], 0, s[16:17]
	s_mov_b64 s[16:17], 0x120200
	v_add_f32_e32 v136, 1.0, v136
	v_add_f32_e32 v137, 1.0, v137
	v_rcp_f32_e32 v136, v136
	v_rcp_f32_e32 v137, v137
	v_lshl_add_u64 v[172:173], v[156:157], 0, s[16:17]
	v_pk_mul_f32 v[186:187], v[20:21], v[146:147] op_sel_hi:[1,0]
	s_mov_b64 s[16:17], 0x120210
	v_pk_fma_f32 v[134:135], v[136:137], v[138:139], v[134:135]
	s_nop 0
	global_store_dwordx4 v[170:171], v[132:135], off sc1
	s_nop 1
	v_cvt_pk_bf16_f32 v136, v128, v129
	v_cvt_pk_bf16_f32 v137, v130, v131
	v_cvt_pk_bf16_f32 v138, v132, v133
	v_cvt_pk_bf16_f32 v139, v134, v135
	v_pk_mul_f32 v[170:171], v[130:131], v[130:131]
	global_store_dwordx4 v[168:169], v[136:139], off sc1
	s_nop 1
	v_pk_mul_f32 v[168:169], v[128:129], v[128:129]
	v_pk_mul_f32 v[138:139], v[132:133], v[132:133]
	v_pk_mul_f32 v[136:137], v[134:135], v[134:135]
	global_load_dwordx4 v[182:185], v[166:167], off offset:512
	global_load_dwordx4 v[128:131], v[172:173], off offset:16
	global_load_dwordx4 v[132:135], v[164:165], off offset:256
	v_pk_mul_f32 v[164:165], v[22:23], v[146:147] op_sel_hi:[1,0]
	v_mul_f32_e32 v146, 0xbfb8aa3b, v186
	v_exp_f32_e32 v146, v146
	v_lshl_add_u64 v[166:167], v[156:157], 0, s[16:17]
	s_mov_b64 s[16:17], 0x90100
	v_add_f32_e32 v161, v168, v169
	v_add_f32_e32 v146, 1.0, v146
	v_rcp_f32_e32 v186, v146
	v_mul_f32_e32 v146, 0xbfb8aa3b, v187
	v_exp_f32_e32 v146, v146
	v_add_f32_e32 v138, v138, v139
	v_add_f32_e32 v136, v136, v137
	v_add_f32_e32 v146, 1.0, v146
	v_rcp_f32_e32 v187, v146
	v_add_f32_e32 v146, v170, v171
	v_add_f32_e32 v146, v161, v146
	v_add_f32_e32 v138, v138, v146
	v_add_f32_e32 v136, v136, v138
	s_waitcnt vmcnt(0)
	v_lshlrev_b32_e32 v192, 16, v132
	v_and_b32_e32 v193, 0xffff0000, v132
	v_mul_f32_e32 v132, 0xbfb8aa3b, v164
	v_exp_f32_e32 v132, v132
	v_pk_fma_f32 v[182:183], v[186:187], v[192:193], v[182:183]
	v_add_f32_e32 v132, 1.0, v132
	v_rcp_f32_e32 v164, v132
	v_mul_f32_e32 v132, 0xbfb8aa3b, v165
	v_exp_f32_e32 v132, v132
	s_nop 0
	v_add_f32_e32 v132, 1.0, v132
	v_rcp_f32_e32 v165, v132
	v_lshlrev_b32_e32 v132, 16, v133
	v_and_b32_e32 v133, 0xffff0000, v133
	v_pk_fma_f32 v[184:185], v[164:165], v[132:133], v[184:185]
	v_mul_f32_e32 v132, 0xbfb8aa3b, v190
	v_mul_f32_e32 v133, 0xbfb8aa3b, v191
	v_exp_f32_e32 v132, v132
	v_exp_f32_e32 v133, v133
	v_lshlrev_b32_e32 v164, 16, v134
	v_and_b32_e32 v165, 0xffff0000, v134
	v_add_f32_e32 v132, 1.0, v132
	v_add_f32_e32 v133, 1.0, v133
	v_rcp_f32_e32 v132, v132
	v_rcp_f32_e32 v133, v133
	v_lshlrev_b32_e32 v134, 16, v135
	v_and_b32_e32 v135, 0xffff0000, v135
	global_store_dwordx4 v[172:173], v[182:185], off sc1
	s_nop 1
	v_pk_fma_f32 v[128:129], v[132:133], v[164:165], v[128:129]
	v_mul_f32_e32 v132, 0xbfb8aa3b, v188
	v_mul_f32_e32 v133, 0xbfb8aa3b, v189
	v_exp_f32_e32 v132, v132
	v_exp_f32_e32 v133, v133
	v_lshl_add_u64 v[164:165], v[154:155], 0, s[16:17]
	v_add_f32_e32 v132, 1.0, v132
	v_add_f32_e32 v133, 1.0, v133
	v_rcp_f32_e32 v132, v132
	v_rcp_f32_e32 v133, v133
	s_nop 0
	v_pk_fma_f32 v[130:131], v[132:133], v[134:135], v[130:131]
	s_nop 0
	global_store_dwordx4 v[166:167], v[128:131], off sc1
	s_nop 1
	v_cvt_pk_bf16_f32 v132, v182, v183
	v_cvt_pk_bf16_f32 v133, v184, v185
	v_cvt_pk_bf16_f32 v134, v128, v129
	v_cvt_pk_bf16_f32 v135, v130, v131
	v_pk_mul_f32 v[128:129], v[128:129], v[128:129]
	global_store_dwordx4 v[164:165], v[132:135], off sc1
	s_nop 1
	v_pk_mul_f32 v[132:133], v[182:183], v[182:183]
	v_pk_mul_f32 v[134:135], v[184:185], v[184:185]
	v_add_f32_e32 v132, v132, v133
	v_add_f32_e32 v134, v134, v135
	v_pk_mul_f32 v[130:131], v[130:131], v[130:131]
	v_add_f32_e32 v132, v132, v134
	v_add_f32_e32 v128, v128, v129
	v_add_f32_e32 v128, v128, v132
	v_add_f32_e32 v129, v130, v131
	v_add_f32_e32 v128, v129, v128
	v_add_f32_e32 v128, v136, v128
	ds_bpermute_b32 v129, v177, v128
	s_waitcnt lgkmcnt(0)
	v_add_f32_e32 v128, v128, v129
	ds_bpermute_b32 v129, v178, v128
	s_and_saveexec_b64 s[16:17], s[6:7]
	s_cbranch_execz .LBB0_731
	v_lshl_add_u64 v[130:131], v[162:163], 2, s[60:61]
	s_waitcnt lgkmcnt(0)
	v_add_f32_e32 v128, v128, v129
	global_atomic_add_f32 v[130:131], v128, off
; __device__ __forceinline__ unsigned cvt_pk_bf16(float lo, float hi) { unsigned r; asm volatile("v_cvt_pk_bf16_f32 %0, %1, %2" : "=v"(r) : "v"(lo), "v"(hi)); return r; }
; template <bool WT> __device__ __forceinline__ void st16(void* p, f32x4 v) { if constexpr (WT) st16_wt(p, v); else *(f32x4*)p = v; }
; __device__ __forceinline__ float rstd_of(float ss) { return __builtin_amdgcn_rsqf(ss * (1.0f / 2048.0f) + NORM_EPS); }
;     __device__ __forceinline__ void operator()(const f32x4 (&acc)[2][2][4][2], const Unit& u, int wr, int wc, int fr, int fq) const {
;     ...
;             for (int m = 0; m < 4; ++m) { const size_t ro = (size_t)(ai * HALF + m * 16) * LD; float sq = 0.f; const int grow = u.pm * BM + ai * HALF + m * 16 + rt; const float rs = rstd_of(ssin[grow]);
; #pragma unroll
;                 for (int bj = 0; bj < 2; ++bj) { const size_t o = obase + ro + bj * HALF; const f32x4 h0 = *(const f32x4*)(H + o), h1 = *(const f32x4*)(H + o + 4); const u32x4 ev = *(const u32x4*)(E + o);
;                     const f32x4 a0 = acc[ai][bj][m][0] * rs, a1 = acc[ai][bj][m][1] * rs; f32x4 v0, v1;
;                     v0[0] = h0[0] + sigmoid_f(a0[0]) * __uint_as_float(ev.x << 16); v0[1] = h0[1] + sigmoid_f(a0[1]) * __uint_as_float(ev.x & 0xffff0000u);
;                     v0[2] = h0[2] + sigmoid_f(a0[2]) * __uint_as_float(ev.y << 16); v0[3] = h0[3] + sigmoid_f(a0[3]) * __uint_as_float(ev.y & 0xffff0000u);
;                     v1[0] = h1[0] + sigmoid_f(a1[0]) * __uint_as_float(ev.z << 16); v1[1] = h1[1] + sigmoid_f(a1[1]) * __uint_as_float(ev.z & 0xffff0000u);
;                     v1[2] = h1[2] + sigmoid_f(a1[2]) * __uint_as_float(ev.w << 16); v1[3] = h1[3] + sigmoid_f(a1[3]) * __uint_as_float(ev.w & 0xffff0000u);
;                     st16<WT>(H + o, v0); st16<WT>(H + o + 4, v1);
;                     if constexpr (WXB) { u32x4 w; w.x = cvt_pk_bf16(v0[0], v0[1]); w.y = cvt_pk_bf16(v0[2], v0[3]); w.z = cvt_pk_bf16(v1[0], v1[1]); w.w = cvt_pk_bf16(v1[2], v1[3]);
;                         st16<WT>(XB + o, __builtin_bit_cast(f32x4, w)); }
;                     sq += (v0[0] * v0[0] + v0[1] * v0[1]) + (v0[2] * v0[2] + v0[3] * v0[3]) + (v1[0] * v1[0] + v1[1] * v1[1]) + (v1[2] * v1[2] + v1[3] * v1[3]); }
;                 sq += __shfl_xor(sq, 16); sq += __shfl_xor(sq, 32);
;                 if (fq == 0) ss_add<false>(ssout + grow, sq);
.LBB0_731:
	s_or_b64 exec, exec, s[16:17]
	v_or_b32_e32 v162, 32, v160
	v_ashrrev_i32_e32 v163, 31, v162
	s_waitcnt lgkmcnt(0)
	v_add_co_u32_e32 v166, vcc, 0x140000, v156
	s_mov_b64 s[16:17], 0x140000
	s_nop 0
	v_addc_co_u32_e32 v167, vcc, 0, v157, vcc
	v_add_co_u32_e32 v164, vcc, 0xa0000, v158
	v_lshl_add_u64 v[168:169], v[156:157], 0, s[16:17]
	s_nop 0
	v_addc_co_u32_e32 v165, vcc, 0, v159, vcc
	s_mov_b64 s[16:17], 0x140010
	v_lshl_add_u64 v[170:171], v[156:157], 0, s[16:17]
	s_mov_b64 s[16:17], 0xa0000
	v_fmamk_f32 v128, v251, 0x3a000000, v181
	v_or_b32_e32 v254, 48, v160
	v_ashrrev_i32_e32 v255, 31, v254
	v_lshl_add_u64 v[252:253], v[254:255], 2, s[58:59]
	global_load_dword v251, v[252:253], off
	v_rsq_f32_e32 v146, v128
	global_load_dwordx4 v[128:131], v[166:167], off
	global_load_dwordx4 v[132:135], v[168:169], off offset:16
	global_load_dwordx4 v[136:139], v[164:165], off
	v_pk_mul_f32 v[172:173], v[46:47], v[146:147] op_sel_hi:[1,0]
	v_pk_mul_f32 v[186:187], v[40:41], v[146:147] op_sel_hi:[1,0]
	v_pk_mul_f32 v[182:183], v[44:45], v[146:147] op_sel_hi:[1,0]
	v_pk_mul_f32 v[184:185], v[42:43], v[146:147] op_sel_hi:[1,0]
	v_mul_f32_e32 v161, 0xbfb8aa3b, v182
	v_exp_f32_e32 v161, v161
	v_pk_mul_f32 v[190:191], v[8:9], v[146:147] op_sel_hi:[1,0]
	v_add_f32_e32 v161, 1.0, v161
	v_rcp_f32_e32 v182, v161
	v_mul_f32_e32 v161, 0xbfb8aa3b, v183
	v_exp_f32_e32 v161, v161
	s_waitcnt vmcnt(0)
	v_lshlrev_b32_e32 v188, 16, v136
	v_and_b32_e32 v189, 0xffff0000, v136
	v_mul_f32_e32 v136, 0xbfb8aa3b, v172
	v_exp_f32_e32 v136, v136
	v_add_f32_e32 v161, 1.0, v161
	v_rcp_f32_e32 v183, v161
	v_add_f32_e32 v136, 1.0, v136
	v_rcp_f32_e32 v172, v136
	v_mul_f32_e32 v136, 0xbfb8aa3b, v173
	v_exp_f32_e32 v136, v136
	v_pk_fma_f32 v[128:129], v[182:183], v[188:189], v[128:129]
	v_pk_mul_f32 v[188:189], v[10:11], v[146:147] op_sel_hi:[1,0]
	v_add_f32_e32 v136, 1.0, v136
	v_rcp_f32_e32 v173, v136
	v_lshlrev_b32_e32 v136, 16, v137
	v_and_b32_e32 v137, 0xffff0000, v137
	v_pk_fma_f32 v[130:131], v[172:173], v[136:137], v[130:131]
	v_mul_f32_e32 v136, 0xbfb8aa3b, v186
	v_mul_f32_e32 v137, 0xbfb8aa3b, v187
	v_exp_f32_e32 v136, v136
	v_exp_f32_e32 v137, v137
	v_lshlrev_b32_e32 v172, 16, v138
	v_and_b32_e32 v173, 0xffff0000, v138
	v_add_f32_e32 v136, 1.0, v136
	v_add_f32_e32 v137, 1.0, v137
	v_rcp_f32_e32 v136, v136
	v_rcp_f32_e32 v137, v137
	v_lshlrev_b32_e32 v138, 16, v139
	v_and_b32_e32 v139, 0xffff0000, v139
	global_store_dwordx4 v[168:169], v[128:131], off sc1
	s_nop 1
	v_pk_fma_f32 v[132:133], v[136:137], v[172:173], v[132:133]
	v_mul_f32_e32 v136, 0xbfb8aa3b, v184
	v_mul_f32_e32 v137, 0xbfb8aa3b, v185
	v_exp_f32_e32 v136, v136
	v_exp_f32_e32 v137, v137
	v_lshl_add_u64 v[168:169], v[154:155], 0, s[16:17]
	s_mov_b64 s[16:17], 0x140200
	v_add_f32_e32 v136, 1.0, v136
	v_add_f32_e32 v137, 1.0, v137
	v_rcp_f32_e32 v136, v136
	v_rcp_f32_e32 v137, v137
	v_lshl_add_u64 v[172:173], v[156:157], 0, s[16:17]
	v_pk_mul_f32 v[186:187], v[12:13], v[146:147] op_sel_hi:[1,0]
	s_mov_b64 s[16:17], 0x140210
	v_pk_fma_f32 v[134:135], v[136:137], v[138:139], v[134:135]
	s_nop 0
	global_store_dwordx4 v[170:171], v[132:135], off sc1
	s_nop 1
	v_cvt_pk_bf16_f32 v136, v128, v129
	v_cvt_pk_bf16_f32 v137, v130, v131
	v_cvt_pk_bf16_f32 v138, v132, v133
	v_cvt_pk_bf16_f32 v139, v134, v135
	v_pk_mul_f32 v[170:171], v[130:131], v[130:131]
	global_store_dwordx4 v[168:169], v[136:139], off sc1
	s_nop 1
	v_pk_mul_f32 v[168:169], v[128:129], v[128:129]
	v_pk_mul_f32 v[138:139], v[132:133], v[132:133]
	v_pk_mul_f32 v[136:137], v[134:135], v[134:135]
	global_load_dwordx4 v[182:185], v[166:167], off offset:512
	global_load_dwordx4 v[128:131], v[172:173], off offset:16
	global_load_dwordx4 v[132:135], v[164:165], off offset:256
	v_pk_mul_f32 v[164:165], v[14:15], v[146:147] op_sel_hi:[1,0]
	v_mul_f32_e32 v146, 0xbfb8aa3b, v186
	v_exp_f32_e32 v146, v146
	v_lshl_add_u64 v[166:167], v[156:157], 0, s[16:17]
	s_mov_b64 s[16:17], 0xa0100
	v_add_f32_e32 v161, v168, v169
	v_add_f32_e32 v146, 1.0, v146
	v_rcp_f32_e32 v186, v146
	v_mul_f32_e32 v146, 0xbfb8aa3b, v187
	v_exp_f32_e32 v146, v146
	v_add_f32_e32 v138, v138, v139
	v_add_f32_e32 v136, v136, v137
	v_add_f32_e32 v146, 1.0, v146
	v_rcp_f32_e32 v187, v146
	v_add_f32_e32 v146, v170, v171
	v_add_f32_e32 v146, v161, v146
	v_add_f32_e32 v138, v138, v146
	v_add_f32_e32 v136, v136, v138
	s_waitcnt vmcnt(0)
	v_lshlrev_b32_e32 v192, 16, v132
	v_and_b32_e32 v193, 0xffff0000, v132
	v_mul_f32_e32 v132, 0xbfb8aa3b, v164
	v_exp_f32_e32 v132, v132
	v_pk_fma_f32 v[182:183], v[186:187], v[192:193], v[182:183]
	v_add_f32_e32 v132, 1.0, v132
	v_rcp_f32_e32 v164, v132
	v_mul_f32_e32 v132, 0xbfb8aa3b, v165
	v_exp_f32_e32 v132, v132
	s_nop 0
	v_add_f32_e32 v132, 1.0, v132
	v_rcp_f32_e32 v165, v132
	v_lshlrev_b32_e32 v132, 16, v133
	v_and_b32_e32 v133, 0xffff0000, v133
	v_pk_fma_f32 v[184:185], v[164:165], v[132:133], v[184:185]
	v_mul_f32_e32 v132, 0xbfb8aa3b, v190
	v_mul_f32_e32 v133, 0xbfb8aa3b, v191
	v_exp_f32_e32 v132, v132
	v_exp_f32_e32 v133, v133
	v_lshlrev_b32_e32 v164, 16, v134
	v_and_b32_e32 v165, 0xffff0000, v134
	v_add_f32_e32 v132, 1.0, v132
	v_add_f32_e32 v133, 1.0, v133
	v_rcp_f32_e32 v132, v132
	v_rcp_f32_e32 v133, v133
	v_lshlrev_b32_e32 v134, 16, v135
	v_and_b32_e32 v135, 0xffff0000, v135
	global_store_dwordx4 v[172:173], v[182:185], off sc1
	s_nop 1
	v_pk_fma_f32 v[128:129], v[132:133], v[164:165], v[128:129]
	v_mul_f32_e32 v132, 0xbfb8aa3b, v188
	v_mul_f32_e32 v133, 0xbfb8aa3b, v189
	v_exp_f32_e32 v132, v132
	v_exp_f32_e32 v133, v133
	v_lshl_add_u64 v[164:165], v[154:155], 0, s[16:17]
	v_add_f32_e32 v132, 1.0, v132
	v_add_f32_e32 v133, 1.0, v133
	v_rcp_f32_e32 v132, v132
	v_rcp_f32_e32 v133, v133
	s_nop 0
	v_pk_fma_f32 v[130:131], v[132:133], v[134:135], v[130:131]
	s_nop 0
	global_store_dwordx4 v[166:167], v[128:131], off sc1
	s_nop 1
	v_cvt_pk_bf16_f32 v132, v182, v183
	v_cvt_pk_bf16_f32 v133, v184, v185
	v_cvt_pk_bf16_f32 v134, v128, v129
	v_cvt_pk_bf16_f32 v135, v130, v131
	v_pk_mul_f32 v[128:129], v[128:129], v[128:129]
	global_store_dwordx4 v[164:165], v[132:135], off sc1
	s_nop 1
	v_pk_mul_f32 v[132:133], v[182:183], v[182:183]
	v_pk_mul_f32 v[134:135], v[184:185], v[184:185]
	v_add_f32_e32 v132, v132, v133
	v_add_f32_e32 v134, v134, v135
	v_pk_mul_f32 v[130:131], v[130:131], v[130:131]
	v_add_f32_e32 v132, v132, v134
	v_add_f32_e32 v128, v128, v129
	v_add_f32_e32 v128, v128, v132
	v_add_f32_e32 v129, v130, v131
	v_add_f32_e32 v128, v129, v128
	v_add_f32_e32 v128, v136, v128
	ds_bpermute_b32 v129, v177, v128
	s_waitcnt lgkmcnt(0)
	v_add_f32_e32 v128, v128, v129
	ds_bpermute_b32 v129, v178, v128
	s_and_saveexec_b64 s[16:17], s[6:7]
	s_cbranch_execz .LBB0_733
	v_lshl_add_u64 v[130:131], v[162:163], 2, s[60:61]
	s_waitcnt lgkmcnt(0)
	v_add_f32_e32 v128, v128, v129
	global_atomic_add_f32 v[130:131], v128, off
; __device__ __forceinline__ unsigned cvt_pk_bf16(float lo, float hi) { unsigned r; asm volatile("v_cvt_pk_bf16_f32 %0, %1, %2" : "=v"(r) : "v"(lo), "v"(hi)); return r; }
; template <bool WT> __device__ __forceinline__ void st16(void* p, f32x4 v) { if constexpr (WT) st16_wt(p, v); else *(f32x4*)p = v; }
; __device__ __forceinline__ float rstd_of(float ss) { return __builtin_amdgcn_rsqf(ss * (1.0f / 2048.0f) + NORM_EPS); }
;     __device__ __forceinline__ void operator()(const f32x4 (&acc)[2][2][4][2], const Unit& u, int wr, int wc, int fr, int fq) const {
;     ...
;             for (int m = 0; m < 4; ++m) { const size_t ro = (size_t)(ai * HALF + m * 16) * LD; float sq = 0.f; const int grow = u.pm * BM + ai * HALF + m * 16 + rt; const float rs = rstd_of(ssin[grow]);
; #pragma unroll
;                 for (int bj = 0; bj < 2; ++bj) { const size_t o = obase + ro + bj * HALF; const f32x4 h0 = *(const f32x4*)(H + o), h1 = *(const f32x4*)(H + o + 4); const u32x4 ev = *(const u32x4*)(E + o);
;                     const f32x4 a0 = acc[ai][bj][m][0] * rs, a1 = acc[ai][bj][m][1] * rs; f32x4 v0, v1;
;                     v0[0] = h0[0] + sigmoid_f(a0[0]) * __uint_as_float(ev.x << 16); v0[1] = h0[1] + sigmoid_f(a0[1]) * __uint_as_float(ev.x & 0xffff0000u);
;                     v0[2] = h0[2] + sigmoid_f(a0[2]) * __uint_as_float(ev.y << 16); v0[3] = h0[3] + sigmoid_f(a0[3]) * __uint_as_float(ev.y & 0xffff0000u);
;                     v1[0] = h1[0] + sigmoid_f(a1[0]) * __uint_as_float(ev.z << 16); v1[1] = h1[1] + sigmoid_f(a1[1]) * __uint_as_float(ev.z & 0xffff0000u);
;                     v1[2] = h1[2] + sigmoid_f(a1[2]) * __uint_as_float(ev.w << 16); v1[3] = h1[3] + sigmoid_f(a1[3]) * __uint_as_float(ev.w & 0xffff0000u);
;                     st16<WT>(H + o, v0); st16<WT>(H + o + 4, v1);
;                     if constexpr (WXB) { u32x4 w; w.x = cvt_pk_bf16(v0[0], v0[1]); w.y = cvt_pk_bf16(v0[2], v0[3]); w.z = cvt_pk_bf16(v1[0], v1[1]); w.w = cvt_pk_bf16(v1[2], v1[3]);
;                         st16<WT>(XB + o, __builtin_bit_cast(f32x4, w)); }
;                     sq += (v0[0] * v0[0] + v0[1] * v0[1]) + (v0[2] * v0[2] + v0[3] * v0[3]) + (v1[0] * v1[0] + v1[1] * v1[1]) + (v1[2] * v1[2] + v1[3] * v1[3]); }
;                 sq += __shfl_xor(sq, 16); sq += __shfl_xor(sq, 32);
;                 if (fq == 0) ss_add<false>(ssout + grow, sq);
.LBB0_733:
	s_or_b64 exec, exec, s[16:17]
	v_or_b32_e32 v160, 48, v160
	v_ashrrev_i32_e32 v161, 31, v160
	s_waitcnt lgkmcnt(0)
	v_add_co_u32_e32 v162, vcc, 0x160000, v156
	s_mov_b64 s[16:17], 0x160000
	s_nop 0
	v_addc_co_u32_e32 v163, vcc, 0, v157, vcc
	v_add_co_u32_e32 v158, vcc, 0xb0000, v158
	v_lshl_add_u64 v[164:165], v[156:157], 0, s[16:17]
	s_nop 0
	v_addc_co_u32_e32 v159, vcc, 0, v159, vcc
	s_mov_b64 s[16:17], 0x160010
	v_lshl_add_u64 v[166:167], v[156:157], 0, s[16:17]
	s_mov_b64 s[16:17], 0xb0000
	v_fmamk_f32 v128, v251, 0x3a000000, v181
	v_rsq_f32_e32 v146, v128
	global_load_dwordx4 v[128:131], v[162:163], off
	global_load_dwordx4 v[132:135], v[164:165], off offset:16
	global_load_dwordx4 v[136:139], v[158:159], off
	v_pk_mul_f32 v[168:169], v[38:39], v[146:147] op_sel_hi:[1,0]
	v_pk_mul_f32 v[182:183], v[32:33], v[146:147] op_sel_hi:[1,0]
	v_pk_mul_f32 v[170:171], v[36:37], v[146:147] op_sel_hi:[1,0]
	v_pk_mul_f32 v[172:173], v[34:35], v[146:147] op_sel_hi:[1,0]
	v_mul_f32_e32 v170, 0xbfb8aa3b, v170
	v_mul_f32_e32 v171, 0xbfb8aa3b, v171
	v_exp_f32_e32 v170, v170
	v_exp_f32_e32 v171, v171
	v_add_f32_e32 v170, 1.0, v170
	v_add_f32_e32 v171, 1.0, v171
	v_rcp_f32_e32 v170, v170
	v_rcp_f32_e32 v171, v171
	s_waitcnt vmcnt(0)
	v_lshlrev_b32_e32 v184, 16, v136
	v_and_b32_e32 v185, 0xffff0000, v136
	v_mul_f32_e32 v136, 0xbfb8aa3b, v168
	v_exp_f32_e32 v136, v136
	v_pk_fma_f32 v[128:129], v[170:171], v[184:185], v[128:129]
	v_pk_mul_f32 v[184:185], v[0:1], v[146:147] op_sel_hi:[1,0]
	v_add_f32_e32 v136, 1.0, v136
	v_rcp_f32_e32 v168, v136
	v_mul_f32_e32 v136, 0xbfb8aa3b, v169
	v_exp_f32_e32 v136, v136
	s_nop 0
	v_add_f32_e32 v136, 1.0, v136
	v_rcp_f32_e32 v169, v136
	v_lshlrev_b32_e32 v136, 16, v137
	v_and_b32_e32 v137, 0xffff0000, v137
	v_pk_fma_f32 v[130:131], v[168:169], v[136:137], v[130:131]
	v_mul_f32_e32 v136, 0xbfb8aa3b, v182
	v_mul_f32_e32 v137, 0xbfb8aa3b, v183
	v_exp_f32_e32 v136, v136
	v_exp_f32_e32 v137, v137
	v_lshlrev_b32_e32 v168, 16, v138
	v_and_b32_e32 v169, 0xffff0000, v138
	v_add_f32_e32 v136, 1.0, v136
	v_add_f32_e32 v137, 1.0, v137
	v_rcp_f32_e32 v136, v136
	v_rcp_f32_e32 v137, v137
	v_lshlrev_b32_e32 v138, 16, v139
	v_and_b32_e32 v139, 0xffff0000, v139
	global_store_dwordx4 v[164:165], v[128:131], off sc1
	s_nop 1
	v_pk_fma_f32 v[132:133], v[136:137], v[168:169], v[132:133]
	v_mul_f32_e32 v136, 0xbfb8aa3b, v172
	v_mul_f32_e32 v137, 0xbfb8aa3b, v173
	v_exp_f32_e32 v136, v136
	v_exp_f32_e32 v137, v137
	v_lshl_add_u64 v[164:165], v[154:155], 0, s[16:17]
	s_mov_b64 s[16:17], 0x160200
	v_add_f32_e32 v136, 1.0, v136
	v_add_f32_e32 v137, 1.0, v137
	v_rcp_f32_e32 v136, v136
	v_rcp_f32_e32 v137, v137
	v_lshl_add_u64 v[168:169], v[156:157], 0, s[16:17]
	v_pk_mul_f32 v[182:183], v[2:3], v[146:147] op_sel_hi:[1,0]
	s_mov_b64 s[16:17], 0x160210
	v_pk_fma_f32 v[134:135], v[136:137], v[138:139], v[134:135]
	v_lshl_add_u64 v[156:157], v[156:157], 0, s[16:17]
	global_store_dwordx4 v[166:167], v[132:135], off sc1
	s_nop 1
	v_cvt_pk_bf16_f32 v136, v128, v129
	v_cvt_pk_bf16_f32 v137, v130, v131
	v_cvt_pk_bf16_f32 v138, v132, v133
	v_cvt_pk_bf16_f32 v139, v134, v135
	v_pk_mul_f32 v[166:167], v[130:131], v[130:131]
	global_store_dwordx4 v[164:165], v[136:139], off sc1
	s_nop 1
	v_pk_mul_f32 v[164:165], v[128:129], v[128:129]
	v_pk_mul_f32 v[138:139], v[132:133], v[132:133]
	v_pk_mul_f32 v[136:137], v[134:135], v[134:135]
	global_load_dwordx4 v[170:173], v[162:163], off offset:512
	global_load_dwordx4 v[128:131], v[168:169], off offset:16
	global_load_dwordx4 v[132:135], v[158:159], off offset:256
	v_pk_mul_f32 v[158:159], v[6:7], v[146:147] op_sel_hi:[1,0]
	v_pk_mul_f32 v[162:163], v[4:5], v[146:147] op_sel_hi:[1,0]
	s_mov_b64 s[16:17], 0xb0100
	v_mul_f32_e32 v146, 0xbfb8aa3b, v162
	v_exp_f32_e32 v146, v146
	v_lshl_add_u64 v[154:155], v[154:155], 0, s[16:17]
	v_add_f32_e32 v138, v138, v139
	v_add_f32_e32 v136, v136, v137
	v_add_f32_e32 v146, 1.0, v146
	v_rcp_f32_e32 v162, v146
	v_mul_f32_e32 v146, 0xbfb8aa3b, v163
	v_exp_f32_e32 v146, v146
	s_waitcnt vmcnt(0)
	v_lshlrev_b32_e32 v186, 16, v132
	v_and_b32_e32 v187, 0xffff0000, v132
	v_mul_f32_e32 v132, 0xbfb8aa3b, v158
	v_exp_f32_e32 v132, v132
	v_add_f32_e32 v146, 1.0, v146
	v_rcp_f32_e32 v163, v146
	v_add_f32_e32 v146, v166, v167
	v_add_f32_e32 v132, 1.0, v132
	v_rcp_f32_e32 v158, v132
	v_mul_f32_e32 v132, 0xbfb8aa3b, v159
	v_exp_f32_e32 v132, v132
	v_pk_fma_f32 v[170:171], v[162:163], v[186:187], v[170:171]
	v_add_f32_e32 v132, 1.0, v132
	v_rcp_f32_e32 v159, v132
	v_lshlrev_b32_e32 v132, 16, v133
	v_and_b32_e32 v133, 0xffff0000, v133
	v_pk_fma_f32 v[172:173], v[158:159], v[132:133], v[172:173]
	v_mul_f32_e32 v132, 0xbfb8aa3b, v184
	v_mul_f32_e32 v133, 0xbfb8aa3b, v185
	v_exp_f32_e32 v132, v132
	v_exp_f32_e32 v133, v133
	v_lshlrev_b32_e32 v158, 16, v134
	v_and_b32_e32 v159, 0xffff0000, v134
	v_add_f32_e32 v132, 1.0, v132
	v_add_f32_e32 v133, 1.0, v133
	v_rcp_f32_e32 v132, v132
	v_rcp_f32_e32 v133, v133
	v_lshlrev_b32_e32 v134, 16, v135
	v_and_b32_e32 v135, 0xffff0000, v135
	global_store_dwordx4 v[168:169], v[170:173], off sc1
	s_nop 1
	v_pk_fma_f32 v[128:129], v[132:133], v[158:159], v[128:129]
	v_mul_f32_e32 v132, 0xbfb8aa3b, v182
	v_mul_f32_e32 v133, 0xbfb8aa3b, v183
	v_exp_f32_e32 v132, v132
	v_exp_f32_e32 v133, v133
	v_add_f32_e32 v132, 1.0, v132
	v_add_f32_e32 v133, 1.0, v133
	v_rcp_f32_e32 v132, v132
	v_rcp_f32_e32 v133, v133
	s_nop 0
	v_pk_fma_f32 v[130:131], v[132:133], v[134:135], v[130:131]
	s_nop 0
	global_store_dwordx4 v[156:157], v[128:131], off sc1
	s_nop 1
	v_cvt_pk_bf16_f32 v132, v170, v171
	v_cvt_pk_bf16_f32 v133, v172, v173
	v_cvt_pk_bf16_f32 v134, v128, v129
	v_cvt_pk_bf16_f32 v135, v130, v131
	v_pk_mul_f32 v[128:129], v[128:129], v[128:129]
	global_store_dwordx4 v[154:155], v[132:135], off sc1
	s_nop 1
	v_pk_mul_f32 v[132:133], v[170:171], v[170:171]
	v_pk_mul_f32 v[134:135], v[172:173], v[172:173]
	v_add_f32_e32 v154, v164, v165
	v_add_f32_e32 v134, v134, v135
	v_add_f32_e32 v132, v132, v133
	v_pk_mul_f32 v[130:131], v[130:131], v[130:131]
	v_add_f32_e32 v146, v154, v146
	v_add_f32_e32 v132, v132, v134
	v_add_f32_e32 v128, v128, v129
	v_add_f32_e32 v138, v138, v146
	v_add_f32_e32 v128, v128, v132
	v_add_f32_e32 v129, v130, v131
	v_add_f32_e32 v136, v136, v138
	v_add_f32_e32 v128, v129, v128
	v_add_f32_e32 v128, v136, v128
	ds_bpermute_b32 v129, v177, v128
	s_waitcnt lgkmcnt(0)
	v_add_f32_e32 v128, v128, v129
	ds_bpermute_b32 v129, v178, v128
	s_and_saveexec_b64 s[16:17], s[6:7]
	s_cbranch_execz .LBB0_735
	v_lshl_add_u64 v[130:131], v[160:161], 2, s[60:61]
	s_waitcnt lgkmcnt(0)
	v_add_f32_e32 v128, v128, v129
	global_atomic_add_f32 v[130:131], v128, off
